# ffn-up epilogue: conv taps requested before the accumulator dump (fragment registers)
# baseline (speedup 1.0000x reference)
.LBB0_920:
	v_and_b32_e32 v244, 15, v0
	v_lshlrev_b32_e64 v246, 7, s5
	v_lshl_add_u32 v244, v244, 3, v246
	v_lshlrev_b32_e32 v244, 2, v244
	global_load_dwordx4 v[176:179], v244, s[12:13]
	global_load_dwordx4 v[180:183], v244, s[12:13] offset:16
	v_add_u32_e32 v245, 0x5800, v244
	global_load_dwordx4 v[184:187], v245, s[12:13]
	global_load_dwordx4 v[188:191], v245, s[12:13] offset:16
	v_add_u32_e32 v245, 0xb000, v244
	global_load_dwordx4 v[192:195], v245, s[12:13]
	global_load_dwordx4 v[196:199], v245, s[12:13] offset:16
	v_add_u32_e32 v245, 0x2c00, v244
	global_load_dwordx4 v[210:213], v245, s[12:13]
	global_load_dwordx4 v[214:217], v245, s[12:13] offset:16
	v_add_u32_e32 v245, 0x8400, v244
	global_load_dwordx4 v[218:221], v245, s[12:13]
	global_load_dwordx4 v[222:225], v245, s[12:13] offset:16
	v_add_u32_e32 v245, 0xdc00, v244
	global_load_dwordx4 v[228:231], v245, s[12:13]
	global_load_dwordx4 v[232:235], v245, s[12:13] offset:16
	global_load_dwordx4 v[200:203], v244, s[14:15]
	global_load_dwordx4 v[204:207], v244, s[14:15] offset:16
	v_add_u32_e32 v245, 0x2c00, v244
	global_load_dwordx4 v[236:239], v245, s[14:15]
	global_load_dwordx4 v[240:243], v245, s[14:15] offset:16
	v_lshl_or_b32 v134, v172, 2, s40
	v_mad_u64_u32 v[146:147], s[6:7], v1, s47, v[134:135]
	v_cvt_pk_bf16_f32 v106, v106, v107
	v_cvt_pk_bf16_f32 v107, v108, v109
	v_cvt_pk_bf16_f32 v98, v98, v99
	v_cvt_pk_bf16_f32 v99, v100, v101
	v_cvt_pk_bf16_f32 v74, v74, v75
	s_nop 0
	v_lshl_add_u32 v1, v146, 1, 0
	v_add_u32_e32 v108, 0x4000, v1
	v_add_u32_e32 v100, 0x6000, v1
	v_cvt_pk_bf16_f32 v66, v66, v67
	v_cvt_pk_bf16_f32 v58, v58, v59
	v_cvt_pk_bf16_f32 v59, v60, v61
	v_add_u32_e32 v60, 0x10820, v1
	v_cvt_pk_bf16_f32 v50, v50, v51
	v_cvt_pk_bf16_f32 v51, v52, v53
	v_add_u32_e32 v52, 0x12920, v1
	v_cvt_pk_bf16_f32 v42, v42, v43
	v_cvt_pk_bf16_f32 v43, v44, v45
	v_add_u32_e32 v44, 0x14a20, v1
	v_cvt_pk_bf16_f32 v34, v34, v35
	v_cvt_pk_bf16_f32 v35, v36, v37
	v_add_u32_e32 v36, 0x16b20, v1
	v_cvt_pk_bf16_f32 v26, v26, v27
	v_cvt_pk_bf16_f32 v27, v28, v29
	v_add_u32_e32 v28, 0x10920, v1
	v_cvt_pk_bf16_f32 v18, v18, v19
	v_cvt_pk_bf16_f32 v19, v20, v21
	v_add_u32_e32 v20, 0x12a20, v1
	v_cvt_pk_bf16_f32 v10, v10, v11
	v_cvt_pk_bf16_f32 v11, v12, v13
	v_add_u32_e32 v12, 0x14b20, v1
	v_cvt_pk_bf16_f32 v126, v126, v127
	v_cvt_pk_bf16_f32 v127, v128, v129
	v_cvt_pk_bf16_f32 v122, v122, v123
	v_cvt_pk_bf16_f32 v123, v124, v125
	ds_write2_b64 v1, v[126:127], v[122:123] offset1:4
	v_cvt_pk_bf16_f32 v114, v114, v115
	v_cvt_pk_bf16_f32 v115, v116, v117
	v_add_u32_e32 v116, 0x2000, v1
	v_cvt_pk_bf16_f32 v94, v94, v95
	v_cvt_pk_bf16_f32 v95, v96, v97
	v_cvt_pk_bf16_f32 v90, v90, v91
	v_cvt_pk_bf16_f32 v91, v92, v93
	ds_write2_b64 v1, v[94:95], v[90:91] offset0:32 offset1:36
	v_cvt_pk_bf16_f32 v78, v78, v79
	v_cvt_pk_bf16_f32 v79, v80, v81
	v_cvt_pk_bf16_f32 v75, v76, v77
	ds_write2_b64 v108, v[78:79], v[74:75] offset0:96 offset1:100
	v_cvt_pk_bf16_f32 v70, v70, v71
	v_cvt_pk_bf16_f32 v71, v72, v73
	v_cvt_pk_bf16_f32 v67, v68, v69
	ds_write2_b64 v100, v[70:71], v[66:67] offset0:128 offset1:132
	v_add_u32_e32 v66, 0x10800, v1
	ds_write_b64 v60, v[58:59]
	v_add_u32_e32 v58, 0x12900, v1
	ds_write_b64 v52, v[50:51]
	v_add_u32_e32 v50, 0x14a00, v1
	ds_write_b64 v44, v[42:43]
	v_add_u32_e32 v42, 0x16b00, v1
	ds_write_b64 v36, v[34:35]
	v_add_u32_e32 v34, 0x10900, v1
	ds_write_b64 v28, v[26:27]
	v_add_u32_e32 v26, 0x12a00, v1
	ds_write_b64 v20, v[18:19]
	v_add_u32_e32 v18, 0x14b00, v1
	ds_write_b64 v12, v[10:11]
	v_add_u32_e32 v10, 0x16c00, v1
	v_cvt_pk_bf16_f32 v2, v2, v3
	v_add_u32_e32 v1, 0x16c20, v1
	v_mov_b32_e32 v74, v0
	v_cvt_pk_bf16_f32 v118, v118, v119
	v_cvt_pk_bf16_f32 v119, v120, v121
	ds_write2_b64 v116, v[118:119], v[114:115] offset0:32 offset1:36
	v_cvt_pk_bf16_f32 v110, v110, v111
	v_cvt_pk_bf16_f32 v111, v112, v113
	ds_write2_b64 v108, v[110:111], v[106:107] offset0:64 offset1:68
	v_cvt_pk_bf16_f32 v102, v102, v103
	v_cvt_pk_bf16_f32 v103, v104, v105
	ds_write2_b64 v100, v[102:103], v[98:99] offset0:96 offset1:100
	v_cvt_pk_bf16_f32 v86, v86, v87
	v_cvt_pk_bf16_f32 v87, v88, v89
	v_cvt_pk_bf16_f32 v82, v82, v83
	v_cvt_pk_bf16_f32 v83, v84, v85
	ds_write2_b64 v116, v[86:87], v[82:83] offset0:64 offset1:68
	v_cvt_pk_bf16_f32 v62, v62, v63
	v_cvt_pk_bf16_f32 v63, v64, v65
	ds_write_b64 v66, v[62:63]
	v_cvt_pk_bf16_f32 v54, v54, v55
	v_cvt_pk_bf16_f32 v55, v56, v57
	ds_write_b64 v58, v[54:55]
	v_cvt_pk_bf16_f32 v46, v46, v47
	v_cvt_pk_bf16_f32 v47, v48, v49
	ds_write_b64 v50, v[46:47]
	v_cvt_pk_bf16_f32 v38, v38, v39
	v_cvt_pk_bf16_f32 v39, v40, v41
	ds_write_b64 v42, v[38:39]
	v_cvt_pk_bf16_f32 v30, v30, v31
	v_cvt_pk_bf16_f32 v31, v32, v33
	ds_write_b64 v34, v[30:31]
	v_cvt_pk_bf16_f32 v22, v22, v23
	v_cvt_pk_bf16_f32 v23, v24, v25
	ds_write_b64 v26, v[22:23]
	v_cvt_pk_bf16_f32 v14, v14, v15
	v_cvt_pk_bf16_f32 v15, v16, v17
	ds_write_b64 v18, v[14:15]
	v_cvt_pk_bf16_f32 v6, v6, v7
	v_cvt_pk_bf16_f32 v7, v8, v9
	ds_write_b64 v10, v[6:7]
	v_cvt_pk_bf16_f32 v3, v4, v5
	ds_write_b64 v1, v[2:3]
	s_waitcnt lgkmcnt(0)
	s_barrier
	v_and_b32_e32 v107, 15, v0
	v_lshrrev_b32_e32 v106, 4, v0
	v_lshrrev_b32_e32 v104, 3, v107
	v_and_b32_e32 v107, 7, v107
	v_lshlrev_b32_e32 v107, 3, v107
	s_lshl_b32 s34, s5, 7
	v_lshl_or_b32 v108, v104, 6, v107
	v_or_b32_e32 v108, s34, v108
	v_lshl_or_b32 v104, v104, 7, v107
	v_lshlrev_b32_e32 v104, 1, v104
	v_mul_u32_u24_e32 v107, 0x1080, v106
	v_add_u32_e32 v104, v104, v107
	s_lshl_b32 s34, s35, 8
	v_lshl_add_u32 v105, v106, 3, s34
	v_mul_u32_u24_e32 v105, 0x1600, v105
	v_lshl_add_u32 v105, v108, 1, v105
	v_mov_b32_e32 v102, 0xbfb8aa3b
	v_mov_b32_e32 v103, 0xbfb8aa3b
	v_cmp_ne_u32_e32 vcc, 0, v106
	s_nop 1
	s_and_saveexec_b64 s[38:39], vcc
	v_add_u32_e32 v107, 0xfffffdf0, v104
	ds_read_b128 v[94:97], v107
	ds_read_b128 v[98:101], v107 offset:128
	s_or_b64 exec, exec, s[38:39]
	s_waitcnt lgkmcnt(0)
	v_lshlrev_b32_e32 v2, 16, v94
	v_and_b32_e32 v3, 0xffff0000, v94
	v_lshlrev_b32_e32 v4, 16, v95
	v_and_b32_e32 v5, 0xffff0000, v95
	v_lshlrev_b32_e32 v6, 16, v96
	v_and_b32_e32 v7, 0xffff0000, v96
	v_lshlrev_b32_e32 v8, 16, v97
	v_and_b32_e32 v9, 0xffff0000, v97
	v_lshlrev_b32_e32 v10, 16, v98
	v_and_b32_e32 v11, 0xffff0000, v98
	v_lshlrev_b32_e32 v12, 16, v99
	v_and_b32_e32 v13, 0xffff0000, v99
	v_lshlrev_b32_e32 v14, 16, v100
	v_and_b32_e32 v15, 0xffff0000, v100
	v_lshlrev_b32_e32 v16, 16, v101
	v_and_b32_e32 v17, 0xffff0000, v101
	v_cmp_eq_u32_e32 vcc, 0, v106
	s_nop 1
	v_cndmask_b32_e64 v2, v2, 0, vcc
	v_cndmask_b32_e64 v3, v3, 0, vcc
	v_cndmask_b32_e64 v4, v4, 0, vcc
	v_cndmask_b32_e64 v5, v5, 0, vcc
	v_cndmask_b32_e64 v6, v6, 0, vcc
	v_cndmask_b32_e64 v7, v7, 0, vcc
	v_cndmask_b32_e64 v8, v8, 0, vcc
	v_cndmask_b32_e64 v9, v9, 0, vcc
	v_cndmask_b32_e64 v10, v10, 0, vcc
	v_cndmask_b32_e64 v11, v11, 0, vcc
	v_cndmask_b32_e64 v12, v12, 0, vcc
	v_cndmask_b32_e64 v13, v13, 0, vcc
	v_cndmask_b32_e64 v14, v14, 0, vcc
	v_cndmask_b32_e64 v15, v15, 0, vcc
	v_cndmask_b32_e64 v16, v16, 0, vcc
	v_cndmask_b32_e64 v17, v17, 0, vcc
	ds_read_b128 v[94:97], v104
	ds_read_b128 v[98:101], v104 offset:128
	s_waitcnt lgkmcnt(0)
	v_lshlrev_b32_e32 v18, 16, v94
	v_and_b32_e32 v19, 0xffff0000, v94
	v_lshlrev_b32_e32 v20, 16, v95
	v_and_b32_e32 v21, 0xffff0000, v95
	v_lshlrev_b32_e32 v22, 16, v96
	v_and_b32_e32 v23, 0xffff0000, v96
	v_lshlrev_b32_e32 v24, 16, v97
	v_and_b32_e32 v25, 0xffff0000, v97
	v_lshlrev_b32_e32 v26, 16, v98
	v_and_b32_e32 v27, 0xffff0000, v98
	v_lshlrev_b32_e32 v28, 16, v99
	v_and_b32_e32 v29, 0xffff0000, v99
	v_lshlrev_b32_e32 v30, 16, v100
	v_and_b32_e32 v31, 0xffff0000, v100
	v_lshlrev_b32_e32 v32, 16, v101
	v_and_b32_e32 v33, 0xffff0000, v101
	ds_read_b128 v[94:97], v104 offset:528
	ds_read_b128 v[98:101], v104 offset:656
	s_waitcnt lgkmcnt(0)
	v_lshlrev_b32_e32 v34, 16, v94
	v_and_b32_e32 v35, 0xffff0000, v94
	v_lshlrev_b32_e32 v36, 16, v95
	v_and_b32_e32 v37, 0xffff0000, v95
	v_lshlrev_b32_e32 v38, 16, v96
	v_and_b32_e32 v39, 0xffff0000, v96
	v_lshlrev_b32_e32 v40, 16, v97
	v_and_b32_e32 v41, 0xffff0000, v97
	v_lshlrev_b32_e32 v42, 16, v98
	v_and_b32_e32 v43, 0xffff0000, v98
	v_lshlrev_b32_e32 v44, 16, v99
	v_and_b32_e32 v45, 0xffff0000, v99
	v_lshlrev_b32_e32 v46, 16, v100
	v_and_b32_e32 v47, 0xffff0000, v100
	v_lshlrev_b32_e32 v48, 16, v101
	v_and_b32_e32 v49, 0xffff0000, v101
	ds_read_b128 v[94:97], v104 offset:1056
	ds_read_b128 v[98:101], v104 offset:1184
	s_waitcnt vmcnt(0)
	v_pk_fma_f32 v[66:67], v[176:177], v[2:3], v[200:201]
	v_pk_fma_f32 v[68:69], v[178:179], v[4:5], v[202:203]
	v_pk_fma_f32 v[70:71], v[180:181], v[6:7], v[204:205]
	v_pk_fma_f32 v[72:73], v[182:183], v[8:9], v[206:207]
	v_pk_fma_f32 v[74:75], v[210:211], v[10:11], v[236:237]
	v_pk_fma_f32 v[76:77], v[212:213], v[12:13], v[238:239]
	v_pk_fma_f32 v[78:79], v[214:215], v[14:15], v[240:241]
	v_pk_fma_f32 v[80:81], v[216:217], v[16:17], v[242:243]
	v_pk_fma_f32 v[66:67], v[184:185], v[18:19], v[66:67]
	v_pk_fma_f32 v[68:69], v[186:187], v[20:21], v[68:69]
	v_pk_fma_f32 v[70:71], v[188:189], v[22:23], v[70:71]
	v_pk_fma_f32 v[72:73], v[190:191], v[24:25], v[72:73]
	v_pk_fma_f32 v[74:75], v[218:219], v[26:27], v[74:75]
	v_pk_fma_f32 v[76:77], v[220:221], v[28:29], v[76:77]
	v_pk_fma_f32 v[78:79], v[222:223], v[30:31], v[78:79]
	v_pk_fma_f32 v[80:81], v[224:225], v[32:33], v[80:81]
	v_pk_fma_f32 v[66:67], v[192:193], v[34:35], v[66:67]
	v_pk_fma_f32 v[68:69], v[194:195], v[36:37], v[68:69]
	v_pk_fma_f32 v[70:71], v[196:197], v[38:39], v[70:71]
	v_pk_fma_f32 v[72:73], v[198:199], v[40:41], v[72:73]
	v_pk_fma_f32 v[74:75], v[228:229], v[42:43], v[74:75]
	v_pk_fma_f32 v[76:77], v[230:231], v[44:45], v[76:77]
	v_pk_fma_f32 v[78:79], v[232:233], v[46:47], v[78:79]
	v_pk_fma_f32 v[80:81], v[234:235], v[48:49], v[80:81]
	v_pk_mul_f32 v[82:83], v[66:67], v[102:103]
	v_pk_mul_f32 v[84:85], v[68:69], v[102:103]
	v_pk_mul_f32 v[86:87], v[70:71], v[102:103]
	v_pk_mul_f32 v[88:89], v[72:73], v[102:103]
	v_exp_f32_e32 v82, v82
	v_exp_f32_e32 v83, v83
	v_exp_f32_e32 v84, v84
	v_exp_f32_e32 v85, v85
	v_exp_f32_e32 v86, v86
	v_exp_f32_e32 v87, v87
	v_exp_f32_e32 v88, v88
	v_exp_f32_e32 v89, v89
	v_pk_add_f32 v[82:83], v[82:83], 1.0 op_sel_hi:[1,0]
	v_pk_add_f32 v[84:85], v[84:85], 1.0 op_sel_hi:[1,0]
	v_pk_add_f32 v[86:87], v[86:87], 1.0 op_sel_hi:[1,0]
	v_pk_add_f32 v[88:89], v[88:89], 1.0 op_sel_hi:[1,0]
	v_rcp_f32_e32 v82, v82
	v_rcp_f32_e32 v83, v83
	v_rcp_f32_e32 v84, v84
	v_rcp_f32_e32 v85, v85
	v_rcp_f32_e32 v86, v86
	v_rcp_f32_e32 v87, v87
	v_rcp_f32_e32 v88, v88
	v_rcp_f32_e32 v89, v89
	s_waitcnt lgkmcnt(0)
	v_lshlrev_b32_e32 v50, 16, v94
	v_and_b32_e32 v51, 0xffff0000, v94
	v_lshlrev_b32_e32 v52, 16, v95
	v_and_b32_e32 v53, 0xffff0000, v95
	v_lshlrev_b32_e32 v54, 16, v96
	v_and_b32_e32 v55, 0xffff0000, v96
	v_lshlrev_b32_e32 v56, 16, v97
	v_and_b32_e32 v57, 0xffff0000, v97
	v_lshlrev_b32_e32 v58, 16, v98
	v_and_b32_e32 v59, 0xffff0000, v98
	v_lshlrev_b32_e32 v60, 16, v99
	v_and_b32_e32 v61, 0xffff0000, v99
	v_lshlrev_b32_e32 v62, 16, v100
	v_and_b32_e32 v63, 0xffff0000, v100
	v_lshlrev_b32_e32 v64, 16, v101
	v_and_b32_e32 v65, 0xffff0000, v101
	ds_read_b128 v[94:97], v104 offset:1584
	ds_read_b128 v[98:101], v104 offset:1712
	v_pk_mul_f32 v[66:67], v[66:67], v[82:83]
	v_pk_mul_f32 v[68:69], v[68:69], v[84:85]
	v_pk_mul_f32 v[70:71], v[70:71], v[86:87]
	v_pk_mul_f32 v[72:73], v[72:73], v[88:89]
	v_pk_mul_f32 v[66:67], v[66:67], v[74:75]
	v_pk_mul_f32 v[68:69], v[68:69], v[76:77]
	v_pk_mul_f32 v[70:71], v[70:71], v[78:79]
	v_pk_mul_f32 v[72:73], v[72:73], v[80:81]
	v_cvt_pk_bf16_f32 v90, v66, v67
	v_cvt_pk_bf16_f32 v91, v68, v69
	v_cvt_pk_bf16_f32 v92, v70, v71
	v_cvt_pk_bf16_f32 v93, v72, v73
	s_and_b32 s36, s35, 3
	s_cmp_eq_u32 s36, 0
	s_cselect_b64 s[38:39], -1, 0
	s_cmp_lt_i32 s35, 32
	s_cselect_b64 vcc, -1, 0
	s_or_b64 s[38:39], s[38:39], vcc
	v_cmp_ne_u32_e32 vcc, 0, v106
	s_nop 1
	s_or_b64 vcc, vcc, s[38:39]
	s_and_saveexec_b64 s[38:39], vcc
	global_store_dwordx4 v105, v[90:93], s[0:1] sc1
	s_or_b64 exec, exec, s[38:39]
	v_add_u32_e32 v105, 0x1600, v105
	v_pk_fma_f32 v[66:67], v[176:177], v[18:19], v[200:201]
	v_pk_fma_f32 v[68:69], v[178:179], v[20:21], v[202:203]
	v_pk_fma_f32 v[70:71], v[180:181], v[22:23], v[204:205]
	v_pk_fma_f32 v[72:73], v[182:183], v[24:25], v[206:207]
	v_pk_fma_f32 v[74:75], v[210:211], v[26:27], v[236:237]
	v_pk_fma_f32 v[76:77], v[212:213], v[28:29], v[238:239]
	v_pk_fma_f32 v[78:79], v[214:215], v[30:31], v[240:241]
	v_pk_fma_f32 v[80:81], v[216:217], v[32:33], v[242:243]
	v_pk_fma_f32 v[66:67], v[184:185], v[34:35], v[66:67]
	v_pk_fma_f32 v[68:69], v[186:187], v[36:37], v[68:69]
	v_pk_fma_f32 v[70:71], v[188:189], v[38:39], v[70:71]
	v_pk_fma_f32 v[72:73], v[190:191], v[40:41], v[72:73]
	v_pk_fma_f32 v[74:75], v[218:219], v[42:43], v[74:75]
	v_pk_fma_f32 v[76:77], v[220:221], v[44:45], v[76:77]
	v_pk_fma_f32 v[78:79], v[222:223], v[46:47], v[78:79]
	v_pk_fma_f32 v[80:81], v[224:225], v[48:49], v[80:81]
	v_pk_fma_f32 v[66:67], v[192:193], v[50:51], v[66:67]
	v_pk_fma_f32 v[68:69], v[194:195], v[52:53], v[68:69]
	v_pk_fma_f32 v[70:71], v[196:197], v[54:55], v[70:71]
	v_pk_fma_f32 v[72:73], v[198:199], v[56:57], v[72:73]
	v_pk_fma_f32 v[74:75], v[228:229], v[58:59], v[74:75]
	v_pk_fma_f32 v[76:77], v[230:231], v[60:61], v[76:77]
	v_pk_fma_f32 v[78:79], v[232:233], v[62:63], v[78:79]
	v_pk_fma_f32 v[80:81], v[234:235], v[64:65], v[80:81]
	v_pk_mul_f32 v[82:83], v[66:67], v[102:103]
	v_pk_mul_f32 v[84:85], v[68:69], v[102:103]
	v_pk_mul_f32 v[86:87], v[70:71], v[102:103]
	v_pk_mul_f32 v[88:89], v[72:73], v[102:103]
	v_exp_f32_e32 v82, v82
	v_exp_f32_e32 v83, v83
	v_exp_f32_e32 v84, v84
	v_exp_f32_e32 v85, v85
	v_exp_f32_e32 v86, v86
	v_exp_f32_e32 v87, v87
	v_exp_f32_e32 v88, v88
	v_exp_f32_e32 v89, v89
	v_pk_add_f32 v[82:83], v[82:83], 1.0 op_sel_hi:[1,0]
	v_pk_add_f32 v[84:85], v[84:85], 1.0 op_sel_hi:[1,0]
	v_pk_add_f32 v[86:87], v[86:87], 1.0 op_sel_hi:[1,0]
	v_pk_add_f32 v[88:89], v[88:89], 1.0 op_sel_hi:[1,0]
	v_rcp_f32_e32 v82, v82
	v_rcp_f32_e32 v83, v83
	v_rcp_f32_e32 v84, v84
	v_rcp_f32_e32 v85, v85
	v_rcp_f32_e32 v86, v86
	v_rcp_f32_e32 v87, v87
	v_rcp_f32_e32 v88, v88
	v_rcp_f32_e32 v89, v89
	s_waitcnt lgkmcnt(0)
	v_lshlrev_b32_e32 v2, 16, v94
	v_and_b32_e32 v3, 0xffff0000, v94
	v_lshlrev_b32_e32 v4, 16, v95
	v_and_b32_e32 v5, 0xffff0000, v95
	v_lshlrev_b32_e32 v6, 16, v96
	v_and_b32_e32 v7, 0xffff0000, v96
	v_lshlrev_b32_e32 v8, 16, v97
	v_and_b32_e32 v9, 0xffff0000, v97
	v_lshlrev_b32_e32 v10, 16, v98
	v_and_b32_e32 v11, 0xffff0000, v98
	v_lshlrev_b32_e32 v12, 16, v99
	v_and_b32_e32 v13, 0xffff0000, v99
	v_lshlrev_b32_e32 v14, 16, v100
	v_and_b32_e32 v15, 0xffff0000, v100
	v_lshlrev_b32_e32 v16, 16, v101
	v_and_b32_e32 v17, 0xffff0000, v101
	ds_read_b128 v[94:97], v104 offset:2112
	ds_read_b128 v[98:101], v104 offset:2240
	v_pk_mul_f32 v[66:67], v[66:67], v[82:83]
	v_pk_mul_f32 v[68:69], v[68:69], v[84:85]
	v_pk_mul_f32 v[70:71], v[70:71], v[86:87]
	v_pk_mul_f32 v[72:73], v[72:73], v[88:89]
	v_pk_mul_f32 v[66:67], v[66:67], v[74:75]
	v_pk_mul_f32 v[68:69], v[68:69], v[76:77]
	v_pk_mul_f32 v[70:71], v[70:71], v[78:79]
	v_pk_mul_f32 v[72:73], v[72:73], v[80:81]
	v_cvt_pk_bf16_f32 v90, v66, v67
	v_cvt_pk_bf16_f32 v91, v68, v69
	v_cvt_pk_bf16_f32 v92, v70, v71
	v_cvt_pk_bf16_f32 v93, v72, v73
	global_store_dwordx4 v105, v[90:93], s[0:1] sc1
	v_add_u32_e32 v105, 0x1600, v105
	v_pk_fma_f32 v[66:67], v[176:177], v[34:35], v[200:201]
	v_pk_fma_f32 v[68:69], v[178:179], v[36:37], v[202:203]
	v_pk_fma_f32 v[70:71], v[180:181], v[38:39], v[204:205]
	v_pk_fma_f32 v[72:73], v[182:183], v[40:41], v[206:207]
	v_pk_fma_f32 v[74:75], v[210:211], v[42:43], v[236:237]
	v_pk_fma_f32 v[76:77], v[212:213], v[44:45], v[238:239]
	v_pk_fma_f32 v[78:79], v[214:215], v[46:47], v[240:241]
	v_pk_fma_f32 v[80:81], v[216:217], v[48:49], v[242:243]
	v_pk_fma_f32 v[66:67], v[184:185], v[50:51], v[66:67]
	v_pk_fma_f32 v[68:69], v[186:187], v[52:53], v[68:69]
	v_pk_fma_f32 v[70:71], v[188:189], v[54:55], v[70:71]
	v_pk_fma_f32 v[72:73], v[190:191], v[56:57], v[72:73]
	v_pk_fma_f32 v[74:75], v[218:219], v[58:59], v[74:75]
	v_pk_fma_f32 v[76:77], v[220:221], v[60:61], v[76:77]
	v_pk_fma_f32 v[78:79], v[222:223], v[62:63], v[78:79]
	v_pk_fma_f32 v[80:81], v[224:225], v[64:65], v[80:81]
	v_pk_fma_f32 v[66:67], v[192:193], v[2:3], v[66:67]
	v_pk_fma_f32 v[68:69], v[194:195], v[4:5], v[68:69]
	v_pk_fma_f32 v[70:71], v[196:197], v[6:7], v[70:71]
	v_pk_fma_f32 v[72:73], v[198:199], v[8:9], v[72:73]
	v_pk_fma_f32 v[74:75], v[228:229], v[10:11], v[74:75]
	v_pk_fma_f32 v[76:77], v[230:231], v[12:13], v[76:77]
	v_pk_fma_f32 v[78:79], v[232:233], v[14:15], v[78:79]
	v_pk_fma_f32 v[80:81], v[234:235], v[16:17], v[80:81]
	v_pk_mul_f32 v[82:83], v[66:67], v[102:103]
	v_pk_mul_f32 v[84:85], v[68:69], v[102:103]
	v_pk_mul_f32 v[86:87], v[70:71], v[102:103]
	v_pk_mul_f32 v[88:89], v[72:73], v[102:103]
	v_exp_f32_e32 v82, v82
	v_exp_f32_e32 v83, v83
	v_exp_f32_e32 v84, v84
	v_exp_f32_e32 v85, v85
	v_exp_f32_e32 v86, v86
	v_exp_f32_e32 v87, v87
	v_exp_f32_e32 v88, v88
	v_exp_f32_e32 v89, v89
	v_pk_add_f32 v[82:83], v[82:83], 1.0 op_sel_hi:[1,0]
	v_pk_add_f32 v[84:85], v[84:85], 1.0 op_sel_hi:[1,0]
	v_pk_add_f32 v[86:87], v[86:87], 1.0 op_sel_hi:[1,0]
	v_pk_add_f32 v[88:89], v[88:89], 1.0 op_sel_hi:[1,0]
	v_rcp_f32_e32 v82, v82
	v_rcp_f32_e32 v83, v83
	v_rcp_f32_e32 v84, v84
	v_rcp_f32_e32 v85, v85
	v_rcp_f32_e32 v86, v86
	v_rcp_f32_e32 v87, v87
	v_rcp_f32_e32 v88, v88
	v_rcp_f32_e32 v89, v89
	s_waitcnt lgkmcnt(0)
	v_lshlrev_b32_e32 v18, 16, v94
	v_and_b32_e32 v19, 0xffff0000, v94
	v_lshlrev_b32_e32 v20, 16, v95
	v_and_b32_e32 v21, 0xffff0000, v95
	v_lshlrev_b32_e32 v22, 16, v96
	v_and_b32_e32 v23, 0xffff0000, v96
	v_lshlrev_b32_e32 v24, 16, v97
	v_and_b32_e32 v25, 0xffff0000, v97
	v_lshlrev_b32_e32 v26, 16, v98
	v_and_b32_e32 v27, 0xffff0000, v98
	v_lshlrev_b32_e32 v28, 16, v99
	v_and_b32_e32 v29, 0xffff0000, v99
	v_lshlrev_b32_e32 v30, 16, v100
	v_and_b32_e32 v31, 0xffff0000, v100
	v_lshlrev_b32_e32 v32, 16, v101
	v_and_b32_e32 v33, 0xffff0000, v101
	ds_read_b128 v[94:97], v104 offset:2640
	ds_read_b128 v[98:101], v104 offset:2768
	v_pk_mul_f32 v[66:67], v[66:67], v[82:83]
	v_pk_mul_f32 v[68:69], v[68:69], v[84:85]
	v_pk_mul_f32 v[70:71], v[70:71], v[86:87]
	v_pk_mul_f32 v[72:73], v[72:73], v[88:89]
	v_pk_mul_f32 v[66:67], v[66:67], v[74:75]
	v_pk_mul_f32 v[68:69], v[68:69], v[76:77]
	v_pk_mul_f32 v[70:71], v[70:71], v[78:79]
	v_pk_mul_f32 v[72:73], v[72:73], v[80:81]
	v_cvt_pk_bf16_f32 v90, v66, v67
	v_cvt_pk_bf16_f32 v91, v68, v69
	v_cvt_pk_bf16_f32 v92, v70, v71
	v_cvt_pk_bf16_f32 v93, v72, v73
	global_store_dwordx4 v105, v[90:93], s[0:1] sc1
	v_add_u32_e32 v105, 0x1600, v105
	v_pk_fma_f32 v[66:67], v[176:177], v[50:51], v[200:201]
	v_pk_fma_f32 v[68:69], v[178:179], v[52:53], v[202:203]
	v_pk_fma_f32 v[70:71], v[180:181], v[54:55], v[204:205]
	v_pk_fma_f32 v[72:73], v[182:183], v[56:57], v[206:207]
	v_pk_fma_f32 v[74:75], v[210:211], v[58:59], v[236:237]
	v_pk_fma_f32 v[76:77], v[212:213], v[60:61], v[238:239]
	v_pk_fma_f32 v[78:79], v[214:215], v[62:63], v[240:241]
	v_pk_fma_f32 v[80:81], v[216:217], v[64:65], v[242:243]
	v_pk_fma_f32 v[66:67], v[184:185], v[2:3], v[66:67]
	v_pk_fma_f32 v[68:69], v[186:187], v[4:5], v[68:69]
	v_pk_fma_f32 v[70:71], v[188:189], v[6:7], v[70:71]
	v_pk_fma_f32 v[72:73], v[190:191], v[8:9], v[72:73]
	v_pk_fma_f32 v[74:75], v[218:219], v[10:11], v[74:75]
	v_pk_fma_f32 v[76:77], v[220:221], v[12:13], v[76:77]
	v_pk_fma_f32 v[78:79], v[222:223], v[14:15], v[78:79]
	v_pk_fma_f32 v[80:81], v[224:225], v[16:17], v[80:81]
	v_pk_fma_f32 v[66:67], v[192:193], v[18:19], v[66:67]
	v_pk_fma_f32 v[68:69], v[194:195], v[20:21], v[68:69]
	v_pk_fma_f32 v[70:71], v[196:197], v[22:23], v[70:71]
	v_pk_fma_f32 v[72:73], v[198:199], v[24:25], v[72:73]
	v_pk_fma_f32 v[74:75], v[228:229], v[26:27], v[74:75]
	v_pk_fma_f32 v[76:77], v[230:231], v[28:29], v[76:77]
	v_pk_fma_f32 v[78:79], v[232:233], v[30:31], v[78:79]
	v_pk_fma_f32 v[80:81], v[234:235], v[32:33], v[80:81]
	v_pk_mul_f32 v[82:83], v[66:67], v[102:103]
	v_pk_mul_f32 v[84:85], v[68:69], v[102:103]
	v_pk_mul_f32 v[86:87], v[70:71], v[102:103]
	v_pk_mul_f32 v[88:89], v[72:73], v[102:103]
	v_exp_f32_e32 v82, v82
	v_exp_f32_e32 v83, v83
	v_exp_f32_e32 v84, v84
	v_exp_f32_e32 v85, v85
	v_exp_f32_e32 v86, v86
	v_exp_f32_e32 v87, v87
	v_exp_f32_e32 v88, v88
	v_exp_f32_e32 v89, v89
	v_pk_add_f32 v[82:83], v[82:83], 1.0 op_sel_hi:[1,0]
	v_pk_add_f32 v[84:85], v[84:85], 1.0 op_sel_hi:[1,0]
	v_pk_add_f32 v[86:87], v[86:87], 1.0 op_sel_hi:[1,0]
	v_pk_add_f32 v[88:89], v[88:89], 1.0 op_sel_hi:[1,0]
	v_rcp_f32_e32 v82, v82
	v_rcp_f32_e32 v83, v83
	v_rcp_f32_e32 v84, v84
	v_rcp_f32_e32 v85, v85
	v_rcp_f32_e32 v86, v86
	v_rcp_f32_e32 v87, v87
	v_rcp_f32_e32 v88, v88
	v_rcp_f32_e32 v89, v89
	s_waitcnt lgkmcnt(0)
	v_lshlrev_b32_e32 v34, 16, v94
	v_and_b32_e32 v35, 0xffff0000, v94
	v_lshlrev_b32_e32 v36, 16, v95
	v_and_b32_e32 v37, 0xffff0000, v95
	v_lshlrev_b32_e32 v38, 16, v96
	v_and_b32_e32 v39, 0xffff0000, v96
	v_lshlrev_b32_e32 v40, 16, v97
	v_and_b32_e32 v41, 0xffff0000, v97
	v_lshlrev_b32_e32 v42, 16, v98
	v_and_b32_e32 v43, 0xffff0000, v98
	v_lshlrev_b32_e32 v44, 16, v99
	v_and_b32_e32 v45, 0xffff0000, v99
	v_lshlrev_b32_e32 v46, 16, v100
	v_and_b32_e32 v47, 0xffff0000, v100
	v_lshlrev_b32_e32 v48, 16, v101
	v_and_b32_e32 v49, 0xffff0000, v101
	ds_read_b128 v[94:97], v104 offset:3168
	ds_read_b128 v[98:101], v104 offset:3296
	v_pk_mul_f32 v[66:67], v[66:67], v[82:83]
	v_pk_mul_f32 v[68:69], v[68:69], v[84:85]
	v_pk_mul_f32 v[70:71], v[70:71], v[86:87]
	v_pk_mul_f32 v[72:73], v[72:73], v[88:89]
	v_pk_mul_f32 v[66:67], v[66:67], v[74:75]
	v_pk_mul_f32 v[68:69], v[68:69], v[76:77]
	v_pk_mul_f32 v[70:71], v[70:71], v[78:79]
	v_pk_mul_f32 v[72:73], v[72:73], v[80:81]
	v_cvt_pk_bf16_f32 v90, v66, v67
	v_cvt_pk_bf16_f32 v91, v68, v69
	v_cvt_pk_bf16_f32 v92, v70, v71
	v_cvt_pk_bf16_f32 v93, v72, v73
	global_store_dwordx4 v105, v[90:93], s[0:1] sc1
	v_add_u32_e32 v105, 0x1600, v105
	v_pk_fma_f32 v[66:67], v[176:177], v[2:3], v[200:201]
	v_pk_fma_f32 v[68:69], v[178:179], v[4:5], v[202:203]
	v_pk_fma_f32 v[70:71], v[180:181], v[6:7], v[204:205]
	v_pk_fma_f32 v[72:73], v[182:183], v[8:9], v[206:207]
	v_pk_fma_f32 v[74:75], v[210:211], v[10:11], v[236:237]
	v_pk_fma_f32 v[76:77], v[212:213], v[12:13], v[238:239]
	v_pk_fma_f32 v[78:79], v[214:215], v[14:15], v[240:241]
	v_pk_fma_f32 v[80:81], v[216:217], v[16:17], v[242:243]
	v_pk_fma_f32 v[66:67], v[184:185], v[18:19], v[66:67]
	v_pk_fma_f32 v[68:69], v[186:187], v[20:21], v[68:69]
	v_pk_fma_f32 v[70:71], v[188:189], v[22:23], v[70:71]
	v_pk_fma_f32 v[72:73], v[190:191], v[24:25], v[72:73]
	v_pk_fma_f32 v[74:75], v[218:219], v[26:27], v[74:75]
	v_pk_fma_f32 v[76:77], v[220:221], v[28:29], v[76:77]
	v_pk_fma_f32 v[78:79], v[222:223], v[30:31], v[78:79]
	v_pk_fma_f32 v[80:81], v[224:225], v[32:33], v[80:81]
	v_pk_fma_f32 v[66:67], v[192:193], v[34:35], v[66:67]
	v_pk_fma_f32 v[68:69], v[194:195], v[36:37], v[68:69]
	v_pk_fma_f32 v[70:71], v[196:197], v[38:39], v[70:71]
	v_pk_fma_f32 v[72:73], v[198:199], v[40:41], v[72:73]
	v_pk_fma_f32 v[74:75], v[228:229], v[42:43], v[74:75]
	v_pk_fma_f32 v[76:77], v[230:231], v[44:45], v[76:77]
	v_pk_fma_f32 v[78:79], v[232:233], v[46:47], v[78:79]
	v_pk_fma_f32 v[80:81], v[234:235], v[48:49], v[80:81]
	v_pk_mul_f32 v[82:83], v[66:67], v[102:103]
	v_pk_mul_f32 v[84:85], v[68:69], v[102:103]
	v_pk_mul_f32 v[86:87], v[70:71], v[102:103]
	v_pk_mul_f32 v[88:89], v[72:73], v[102:103]
	v_exp_f32_e32 v82, v82
	v_exp_f32_e32 v83, v83
	v_exp_f32_e32 v84, v84
	v_exp_f32_e32 v85, v85
	v_exp_f32_e32 v86, v86
	v_exp_f32_e32 v87, v87
	v_exp_f32_e32 v88, v88
	v_exp_f32_e32 v89, v89
	v_pk_add_f32 v[82:83], v[82:83], 1.0 op_sel_hi:[1,0]
	v_pk_add_f32 v[84:85], v[84:85], 1.0 op_sel_hi:[1,0]
	v_pk_add_f32 v[86:87], v[86:87], 1.0 op_sel_hi:[1,0]
	v_pk_add_f32 v[88:89], v[88:89], 1.0 op_sel_hi:[1,0]
	v_rcp_f32_e32 v82, v82
	v_rcp_f32_e32 v83, v83
	v_rcp_f32_e32 v84, v84
	v_rcp_f32_e32 v85, v85
	v_rcp_f32_e32 v86, v86
	v_rcp_f32_e32 v87, v87
	v_rcp_f32_e32 v88, v88
	v_rcp_f32_e32 v89, v89
	s_waitcnt lgkmcnt(0)
	v_lshlrev_b32_e32 v50, 16, v94
	v_and_b32_e32 v51, 0xffff0000, v94
	v_lshlrev_b32_e32 v52, 16, v95
	v_and_b32_e32 v53, 0xffff0000, v95
	v_lshlrev_b32_e32 v54, 16, v96
	v_and_b32_e32 v55, 0xffff0000, v96
	v_lshlrev_b32_e32 v56, 16, v97
	v_and_b32_e32 v57, 0xffff0000, v97
	v_lshlrev_b32_e32 v58, 16, v98
	v_and_b32_e32 v59, 0xffff0000, v98
	v_lshlrev_b32_e32 v60, 16, v99
	v_and_b32_e32 v61, 0xffff0000, v99
	v_lshlrev_b32_e32 v62, 16, v100
	v_and_b32_e32 v63, 0xffff0000, v100
	v_lshlrev_b32_e32 v64, 16, v101
	v_and_b32_e32 v65, 0xffff0000, v101
	ds_read_b128 v[94:97], v104 offset:3696
	ds_read_b128 v[98:101], v104 offset:3824
	v_pk_mul_f32 v[66:67], v[66:67], v[82:83]
	v_pk_mul_f32 v[68:69], v[68:69], v[84:85]
	v_pk_mul_f32 v[70:71], v[70:71], v[86:87]
	v_pk_mul_f32 v[72:73], v[72:73], v[88:89]
	v_pk_mul_f32 v[66:67], v[66:67], v[74:75]
	v_pk_mul_f32 v[68:69], v[68:69], v[76:77]
	v_pk_mul_f32 v[70:71], v[70:71], v[78:79]
	v_pk_mul_f32 v[72:73], v[72:73], v[80:81]
	v_cvt_pk_bf16_f32 v90, v66, v67
	v_cvt_pk_bf16_f32 v91, v68, v69
	v_cvt_pk_bf16_f32 v92, v70, v71
	v_cvt_pk_bf16_f32 v93, v72, v73
	global_store_dwordx4 v105, v[90:93], s[0:1] sc1
	v_add_u32_e32 v105, 0x1600, v105
	v_pk_fma_f32 v[66:67], v[176:177], v[18:19], v[200:201]
	v_pk_fma_f32 v[68:69], v[178:179], v[20:21], v[202:203]
	v_pk_fma_f32 v[70:71], v[180:181], v[22:23], v[204:205]
	v_pk_fma_f32 v[72:73], v[182:183], v[24:25], v[206:207]
	v_pk_fma_f32 v[74:75], v[210:211], v[26:27], v[236:237]
	v_pk_fma_f32 v[76:77], v[212:213], v[28:29], v[238:239]
	v_pk_fma_f32 v[78:79], v[214:215], v[30:31], v[240:241]
	v_pk_fma_f32 v[80:81], v[216:217], v[32:33], v[242:243]
	v_pk_fma_f32 v[66:67], v[184:185], v[34:35], v[66:67]
	v_pk_fma_f32 v[68:69], v[186:187], v[36:37], v[68:69]
	v_pk_fma_f32 v[70:71], v[188:189], v[38:39], v[70:71]
	v_pk_fma_f32 v[72:73], v[190:191], v[40:41], v[72:73]
	v_pk_fma_f32 v[74:75], v[218:219], v[42:43], v[74:75]
	v_pk_fma_f32 v[76:77], v[220:221], v[44:45], v[76:77]
	v_pk_fma_f32 v[78:79], v[222:223], v[46:47], v[78:79]
	v_pk_fma_f32 v[80:81], v[224:225], v[48:49], v[80:81]
	v_pk_fma_f32 v[66:67], v[192:193], v[50:51], v[66:67]
	v_pk_fma_f32 v[68:69], v[194:195], v[52:53], v[68:69]
	v_pk_fma_f32 v[70:71], v[196:197], v[54:55], v[70:71]
	v_pk_fma_f32 v[72:73], v[198:199], v[56:57], v[72:73]
	v_pk_fma_f32 v[74:75], v[228:229], v[58:59], v[74:75]
	v_pk_fma_f32 v[76:77], v[230:231], v[60:61], v[76:77]
	v_pk_fma_f32 v[78:79], v[232:233], v[62:63], v[78:79]
	v_pk_fma_f32 v[80:81], v[234:235], v[64:65], v[80:81]
	v_pk_mul_f32 v[82:83], v[66:67], v[102:103]
	v_pk_mul_f32 v[84:85], v[68:69], v[102:103]
	v_pk_mul_f32 v[86:87], v[70:71], v[102:103]
	v_pk_mul_f32 v[88:89], v[72:73], v[102:103]
	v_exp_f32_e32 v82, v82
	v_exp_f32_e32 v83, v83
	v_exp_f32_e32 v84, v84
	v_exp_f32_e32 v85, v85
	v_exp_f32_e32 v86, v86
	v_exp_f32_e32 v87, v87
	v_exp_f32_e32 v88, v88
	v_exp_f32_e32 v89, v89
	v_pk_add_f32 v[82:83], v[82:83], 1.0 op_sel_hi:[1,0]
	v_pk_add_f32 v[84:85], v[84:85], 1.0 op_sel_hi:[1,0]
	v_pk_add_f32 v[86:87], v[86:87], 1.0 op_sel_hi:[1,0]
	v_pk_add_f32 v[88:89], v[88:89], 1.0 op_sel_hi:[1,0]
	v_rcp_f32_e32 v82, v82
	v_rcp_f32_e32 v83, v83
	v_rcp_f32_e32 v84, v84
	v_rcp_f32_e32 v85, v85
	v_rcp_f32_e32 v86, v86
	v_rcp_f32_e32 v87, v87
	v_rcp_f32_e32 v88, v88
	v_rcp_f32_e32 v89, v89
	s_waitcnt lgkmcnt(0)
	v_lshlrev_b32_e32 v2, 16, v94
	v_and_b32_e32 v3, 0xffff0000, v94
	v_lshlrev_b32_e32 v4, 16, v95
	v_and_b32_e32 v5, 0xffff0000, v95
	v_lshlrev_b32_e32 v6, 16, v96
	v_and_b32_e32 v7, 0xffff0000, v96
	v_lshlrev_b32_e32 v8, 16, v97
	v_and_b32_e32 v9, 0xffff0000, v97
	v_lshlrev_b32_e32 v10, 16, v98
	v_and_b32_e32 v11, 0xffff0000, v98
	v_lshlrev_b32_e32 v12, 16, v99
	v_and_b32_e32 v13, 0xffff0000, v99
	v_lshlrev_b32_e32 v14, 16, v100
	v_and_b32_e32 v15, 0xffff0000, v100
	v_lshlrev_b32_e32 v16, 16, v101
	v_and_b32_e32 v17, 0xffff0000, v101
	v_cmp_ne_u32_e32 vcc, 31, v106
	s_nop 1
	s_and_saveexec_b64 s[38:39], vcc
	ds_read_b128 v[94:97], v104 offset:4224
	ds_read_b128 v[98:101], v104 offset:4352
	s_or_b64 exec, exec, s[38:39]
	v_pk_mul_f32 v[66:67], v[66:67], v[82:83]
	v_pk_mul_f32 v[68:69], v[68:69], v[84:85]
	v_pk_mul_f32 v[70:71], v[70:71], v[86:87]
	v_pk_mul_f32 v[72:73], v[72:73], v[88:89]
	v_pk_mul_f32 v[66:67], v[66:67], v[74:75]
	v_pk_mul_f32 v[68:69], v[68:69], v[76:77]
	v_pk_mul_f32 v[70:71], v[70:71], v[78:79]
	v_pk_mul_f32 v[72:73], v[72:73], v[80:81]
	v_cvt_pk_bf16_f32 v90, v66, v67
	v_cvt_pk_bf16_f32 v91, v68, v69
	v_cvt_pk_bf16_f32 v92, v70, v71
	v_cvt_pk_bf16_f32 v93, v72, v73
	global_store_dwordx4 v105, v[90:93], s[0:1] sc1
	v_add_u32_e32 v105, 0x1600, v105
	v_pk_fma_f32 v[66:67], v[176:177], v[34:35], v[200:201]
	v_pk_fma_f32 v[68:69], v[178:179], v[36:37], v[202:203]
	v_pk_fma_f32 v[70:71], v[180:181], v[38:39], v[204:205]
	v_pk_fma_f32 v[72:73], v[182:183], v[40:41], v[206:207]
	v_pk_fma_f32 v[74:75], v[210:211], v[42:43], v[236:237]
	v_pk_fma_f32 v[76:77], v[212:213], v[44:45], v[238:239]
	v_pk_fma_f32 v[78:79], v[214:215], v[46:47], v[240:241]
	v_pk_fma_f32 v[80:81], v[216:217], v[48:49], v[242:243]
	v_pk_fma_f32 v[66:67], v[184:185], v[50:51], v[66:67]
	v_pk_fma_f32 v[68:69], v[186:187], v[52:53], v[68:69]
	v_pk_fma_f32 v[70:71], v[188:189], v[54:55], v[70:71]
	v_pk_fma_f32 v[72:73], v[190:191], v[56:57], v[72:73]
	v_pk_fma_f32 v[74:75], v[218:219], v[58:59], v[74:75]
	v_pk_fma_f32 v[76:77], v[220:221], v[60:61], v[76:77]
	v_pk_fma_f32 v[78:79], v[222:223], v[62:63], v[78:79]
	v_pk_fma_f32 v[80:81], v[224:225], v[64:65], v[80:81]
	v_pk_fma_f32 v[66:67], v[192:193], v[2:3], v[66:67]
	v_pk_fma_f32 v[68:69], v[194:195], v[4:5], v[68:69]
	v_pk_fma_f32 v[70:71], v[196:197], v[6:7], v[70:71]
	v_pk_fma_f32 v[72:73], v[198:199], v[8:9], v[72:73]
	v_pk_fma_f32 v[74:75], v[228:229], v[10:11], v[74:75]
	v_pk_fma_f32 v[76:77], v[230:231], v[12:13], v[76:77]
	v_pk_fma_f32 v[78:79], v[232:233], v[14:15], v[78:79]
	v_pk_fma_f32 v[80:81], v[234:235], v[16:17], v[80:81]
	v_pk_mul_f32 v[82:83], v[66:67], v[102:103]
	v_pk_mul_f32 v[84:85], v[68:69], v[102:103]
	v_pk_mul_f32 v[86:87], v[70:71], v[102:103]
	v_pk_mul_f32 v[88:89], v[72:73], v[102:103]
	v_exp_f32_e32 v82, v82
	v_exp_f32_e32 v83, v83
	v_exp_f32_e32 v84, v84
	v_exp_f32_e32 v85, v85
	v_exp_f32_e32 v86, v86
	v_exp_f32_e32 v87, v87
	v_exp_f32_e32 v88, v88
	v_exp_f32_e32 v89, v89
	v_pk_add_f32 v[82:83], v[82:83], 1.0 op_sel_hi:[1,0]
	v_pk_add_f32 v[84:85], v[84:85], 1.0 op_sel_hi:[1,0]
	v_pk_add_f32 v[86:87], v[86:87], 1.0 op_sel_hi:[1,0]
	v_pk_add_f32 v[88:89], v[88:89], 1.0 op_sel_hi:[1,0]
	v_rcp_f32_e32 v82, v82
	v_rcp_f32_e32 v83, v83
	v_rcp_f32_e32 v84, v84
	v_rcp_f32_e32 v85, v85
	v_rcp_f32_e32 v86, v86
	v_rcp_f32_e32 v87, v87
	v_rcp_f32_e32 v88, v88
	v_rcp_f32_e32 v89, v89
	s_waitcnt lgkmcnt(0)
	v_lshlrev_b32_e32 v18, 16, v94
	v_and_b32_e32 v19, 0xffff0000, v94
	v_lshlrev_b32_e32 v20, 16, v95
	v_and_b32_e32 v21, 0xffff0000, v95
	v_lshlrev_b32_e32 v22, 16, v96
	v_and_b32_e32 v23, 0xffff0000, v96
	v_lshlrev_b32_e32 v24, 16, v97
	v_and_b32_e32 v25, 0xffff0000, v97
	v_lshlrev_b32_e32 v26, 16, v98
	v_and_b32_e32 v27, 0xffff0000, v98
	v_lshlrev_b32_e32 v28, 16, v99
	v_and_b32_e32 v29, 0xffff0000, v99
	v_lshlrev_b32_e32 v30, 16, v100
	v_and_b32_e32 v31, 0xffff0000, v100
	v_lshlrev_b32_e32 v32, 16, v101
	v_and_b32_e32 v33, 0xffff0000, v101
	v_cmp_eq_u32_e32 vcc, 31, v106
	s_nop 1
	v_cndmask_b32_e64 v18, v18, 0, vcc
	v_cndmask_b32_e64 v19, v19, 0, vcc
	v_cndmask_b32_e64 v20, v20, 0, vcc
	v_cndmask_b32_e64 v21, v21, 0, vcc
	v_cndmask_b32_e64 v22, v22, 0, vcc
	v_cndmask_b32_e64 v23, v23, 0, vcc
	v_cndmask_b32_e64 v24, v24, 0, vcc
	v_cndmask_b32_e64 v25, v25, 0, vcc
	v_cndmask_b32_e64 v26, v26, 0, vcc
	v_cndmask_b32_e64 v27, v27, 0, vcc
	v_cndmask_b32_e64 v28, v28, 0, vcc
	v_cndmask_b32_e64 v29, v29, 0, vcc
	v_cndmask_b32_e64 v30, v30, 0, vcc
	v_cndmask_b32_e64 v31, v31, 0, vcc
	v_cndmask_b32_e64 v32, v32, 0, vcc
	v_cndmask_b32_e64 v33, v33, 0, vcc
	v_pk_mul_f32 v[66:67], v[66:67], v[82:83]
	v_pk_mul_f32 v[68:69], v[68:69], v[84:85]
	v_pk_mul_f32 v[70:71], v[70:71], v[86:87]
	v_pk_mul_f32 v[72:73], v[72:73], v[88:89]
	v_pk_mul_f32 v[66:67], v[66:67], v[74:75]
	v_pk_mul_f32 v[68:69], v[68:69], v[76:77]
	v_pk_mul_f32 v[70:71], v[70:71], v[78:79]
	v_pk_mul_f32 v[72:73], v[72:73], v[80:81]
	v_cvt_pk_bf16_f32 v90, v66, v67
	v_cvt_pk_bf16_f32 v91, v68, v69
	v_cvt_pk_bf16_f32 v92, v70, v71
	v_cvt_pk_bf16_f32 v93, v72, v73
	global_store_dwordx4 v105, v[90:93], s[0:1] sc1
	v_add_u32_e32 v105, 0x1600, v105
	v_pk_fma_f32 v[66:67], v[176:177], v[50:51], v[200:201]
	v_pk_fma_f32 v[68:69], v[178:179], v[52:53], v[202:203]
	v_pk_fma_f32 v[70:71], v[180:181], v[54:55], v[204:205]
	v_pk_fma_f32 v[72:73], v[182:183], v[56:57], v[206:207]
	v_pk_fma_f32 v[74:75], v[210:211], v[58:59], v[236:237]
	v_pk_fma_f32 v[76:77], v[212:213], v[60:61], v[238:239]
	v_pk_fma_f32 v[78:79], v[214:215], v[62:63], v[240:241]
	v_pk_fma_f32 v[80:81], v[216:217], v[64:65], v[242:243]
	v_pk_fma_f32 v[66:67], v[184:185], v[2:3], v[66:67]
	v_pk_fma_f32 v[68:69], v[186:187], v[4:5], v[68:69]
	v_pk_fma_f32 v[70:71], v[188:189], v[6:7], v[70:71]
	v_pk_fma_f32 v[72:73], v[190:191], v[8:9], v[72:73]
	v_pk_fma_f32 v[74:75], v[218:219], v[10:11], v[74:75]
	v_pk_fma_f32 v[76:77], v[220:221], v[12:13], v[76:77]
	v_pk_fma_f32 v[78:79], v[222:223], v[14:15], v[78:79]
	v_pk_fma_f32 v[80:81], v[224:225], v[16:17], v[80:81]
	v_pk_fma_f32 v[66:67], v[192:193], v[18:19], v[66:67]
	v_pk_fma_f32 v[68:69], v[194:195], v[20:21], v[68:69]
	v_pk_fma_f32 v[70:71], v[196:197], v[22:23], v[70:71]
	v_pk_fma_f32 v[72:73], v[198:199], v[24:25], v[72:73]
	v_pk_fma_f32 v[74:75], v[228:229], v[26:27], v[74:75]
	v_pk_fma_f32 v[76:77], v[230:231], v[28:29], v[76:77]
	v_pk_fma_f32 v[78:79], v[232:233], v[30:31], v[78:79]
	v_pk_fma_f32 v[80:81], v[234:235], v[32:33], v[80:81]
	v_pk_mul_f32 v[82:83], v[66:67], v[102:103]
	v_pk_mul_f32 v[84:85], v[68:69], v[102:103]
	v_pk_mul_f32 v[86:87], v[70:71], v[102:103]
	v_pk_mul_f32 v[88:89], v[72:73], v[102:103]
	v_exp_f32_e32 v82, v82
	v_exp_f32_e32 v83, v83
	v_exp_f32_e32 v84, v84
	v_exp_f32_e32 v85, v85
	v_exp_f32_e32 v86, v86
	v_exp_f32_e32 v87, v87
	v_exp_f32_e32 v88, v88
	v_exp_f32_e32 v89, v89
	v_pk_add_f32 v[82:83], v[82:83], 1.0 op_sel_hi:[1,0]
	v_pk_add_f32 v[84:85], v[84:85], 1.0 op_sel_hi:[1,0]
	v_pk_add_f32 v[86:87], v[86:87], 1.0 op_sel_hi:[1,0]
	v_pk_add_f32 v[88:89], v[88:89], 1.0 op_sel_hi:[1,0]
	v_rcp_f32_e32 v82, v82
	v_rcp_f32_e32 v83, v83
	v_rcp_f32_e32 v84, v84
	v_rcp_f32_e32 v85, v85
	v_rcp_f32_e32 v86, v86
	v_rcp_f32_e32 v87, v87
	v_rcp_f32_e32 v88, v88
	v_rcp_f32_e32 v89, v89
	v_pk_mul_f32 v[66:67], v[66:67], v[82:83]
	v_pk_mul_f32 v[68:69], v[68:69], v[84:85]
	v_pk_mul_f32 v[70:71], v[70:71], v[86:87]
	v_pk_mul_f32 v[72:73], v[72:73], v[88:89]
	v_pk_mul_f32 v[66:67], v[66:67], v[74:75]
	v_pk_mul_f32 v[68:69], v[68:69], v[76:77]
	v_pk_mul_f32 v[70:71], v[70:71], v[78:79]
	v_pk_mul_f32 v[72:73], v[72:73], v[80:81]
	v_cvt_pk_bf16_f32 v90, v66, v67
	v_cvt_pk_bf16_f32 v91, v68, v69
	v_cvt_pk_bf16_f32 v92, v70, v71
	v_cvt_pk_bf16_f32 v93, v72, v73
	s_and_b32 s36, s35, 3
	s_cmp_eq_u32 s36, 3
	s_cselect_b64 s[38:39], -1, 0
	s_cmp_lt_i32 s35, 32
	s_cselect_b64 vcc, -1, 0
	s_or_b64 s[38:39], s[38:39], vcc
	v_cmp_ne_u32_e32 vcc, 31, v106
	s_nop 1
	s_or_b64 vcc, vcc, s[38:39]
	s_and_saveexec_b64 s[38:39], vcc
	global_store_dwordx4 v105, v[90:93], s[0:1] sc1
	s_or_b64 exec, exec, s[38:39]
	v_mov_b32_e32 v74, v0
	s_cmp_lt_i32 s35, 32
	s_cselect_b64 s[6:7], -1, 0
	s_mov_b64 s[8:9], exec

.LBB0_1794:
	v_and_b32_e32 v244, 15, v0
	v_lshlrev_b32_e64 v246, 7, s15
	v_lshl_add_u32 v244, v244, 3, v246
	v_lshlrev_b32_e32 v244, 2, v244
	global_load_dwordx4 v[176:179], v244, s[0:1]
	global_load_dwordx4 v[180:183], v244, s[0:1] offset:16
	v_add_u32_e32 v245, 0x5800, v244
	global_load_dwordx4 v[184:187], v245, s[0:1]
	global_load_dwordx4 v[188:191], v245, s[0:1] offset:16
	v_add_u32_e32 v245, 0xb000, v244
	global_load_dwordx4 v[192:195], v245, s[0:1]
	global_load_dwordx4 v[196:199], v245, s[0:1] offset:16
	v_add_u32_e32 v245, 0x2c00, v244
	global_load_dwordx4 v[210:213], v245, s[0:1]
	global_load_dwordx4 v[214:217], v245, s[0:1] offset:16
	v_add_u32_e32 v245, 0x8400, v244
	global_load_dwordx4 v[218:221], v245, s[0:1]
	global_load_dwordx4 v[222:225], v245, s[0:1] offset:16
	v_add_u32_e32 v245, 0xdc00, v244
	global_load_dwordx4 v[228:231], v245, s[0:1]
	global_load_dwordx4 v[232:235], v245, s[0:1] offset:16
	global_load_dwordx4 v[200:203], v244, s[10:11]
	global_load_dwordx4 v[204:207], v244, s[10:11] offset:16
	v_add_u32_e32 v245, 0x2c00, v244
	global_load_dwordx4 v[236:239], v245, s[10:11]
	global_load_dwordx4 v[240:243], v245, s[10:11] offset:16
	v_lshl_or_b32 v138, v172, 2, s40
	v_mad_u64_u32 v[150:151], s[4:5], v1, s47, v[138:139]
	v_cvt_pk_bf16_f32 v106, v106, v107
	v_cvt_pk_bf16_f32 v107, v108, v109
	v_cvt_pk_bf16_f32 v98, v98, v99
	v_cvt_pk_bf16_f32 v99, v100, v101
	v_cvt_pk_bf16_f32 v74, v74, v75
	s_nop 0
	v_lshl_add_u32 v1, v150, 1, 0
	v_add_u32_e32 v108, 0x4000, v1
	v_add_u32_e32 v100, 0x6000, v1
	v_cvt_pk_bf16_f32 v66, v66, v67
	v_cvt_pk_bf16_f32 v58, v58, v59
	v_cvt_pk_bf16_f32 v59, v60, v61
	v_add_u32_e32 v60, 0x10820, v1
	v_cvt_pk_bf16_f32 v50, v50, v51
	v_cvt_pk_bf16_f32 v51, v52, v53
	v_add_u32_e32 v52, 0x12920, v1
	v_cvt_pk_bf16_f32 v42, v42, v43
	v_cvt_pk_bf16_f32 v43, v44, v45
	v_add_u32_e32 v44, 0x14a20, v1
	v_cvt_pk_bf16_f32 v34, v34, v35
	v_cvt_pk_bf16_f32 v35, v36, v37
	v_add_u32_e32 v36, 0x16b20, v1
	v_cvt_pk_bf16_f32 v26, v26, v27
	v_cvt_pk_bf16_f32 v27, v28, v29
	v_add_u32_e32 v28, 0x10920, v1
	v_cvt_pk_bf16_f32 v18, v18, v19
	v_cvt_pk_bf16_f32 v19, v20, v21
	v_add_u32_e32 v20, 0x12a20, v1
	v_cvt_pk_bf16_f32 v10, v10, v11
	v_cvt_pk_bf16_f32 v11, v12, v13
	v_add_u32_e32 v12, 0x14b20, v1
	v_cvt_pk_bf16_f32 v126, v126, v127
	v_cvt_pk_bf16_f32 v127, v128, v129
	v_cvt_pk_bf16_f32 v122, v122, v123
	v_cvt_pk_bf16_f32 v123, v124, v125
	ds_write2_b64 v1, v[126:127], v[122:123] offset1:4
	v_cvt_pk_bf16_f32 v114, v114, v115
	v_cvt_pk_bf16_f32 v115, v116, v117
	v_add_u32_e32 v116, 0x2000, v1
	v_cvt_pk_bf16_f32 v94, v94, v95
	v_cvt_pk_bf16_f32 v95, v96, v97
	v_cvt_pk_bf16_f32 v90, v90, v91
	v_cvt_pk_bf16_f32 v91, v92, v93
	ds_write2_b64 v1, v[94:95], v[90:91] offset0:32 offset1:36
	v_cvt_pk_bf16_f32 v78, v78, v79
	v_cvt_pk_bf16_f32 v79, v80, v81
	v_cvt_pk_bf16_f32 v75, v76, v77
	ds_write2_b64 v108, v[78:79], v[74:75] offset0:96 offset1:100
	v_cvt_pk_bf16_f32 v70, v70, v71
	v_cvt_pk_bf16_f32 v71, v72, v73
	v_cvt_pk_bf16_f32 v67, v68, v69
	ds_write2_b64 v100, v[70:71], v[66:67] offset0:128 offset1:132
	v_add_u32_e32 v66, 0x10800, v1
	ds_write_b64 v60, v[58:59]
	v_add_u32_e32 v58, 0x12900, v1
	ds_write_b64 v52, v[50:51]
	v_add_u32_e32 v50, 0x14a00, v1
	ds_write_b64 v44, v[42:43]
	v_add_u32_e32 v42, 0x16b00, v1
	ds_write_b64 v36, v[34:35]
	v_add_u32_e32 v34, 0x10900, v1
	ds_write_b64 v28, v[26:27]
	v_add_u32_e32 v26, 0x12a00, v1
	ds_write_b64 v20, v[18:19]
	v_add_u32_e32 v18, 0x14b00, v1
	ds_write_b64 v12, v[10:11]
	v_add_u32_e32 v10, 0x16c00, v1
	v_cvt_pk_bf16_f32 v2, v2, v3
	v_add_u32_e32 v1, 0x16c20, v1
	v_mov_b32_e32 v74, v0
	v_cvt_pk_bf16_f32 v118, v118, v119
	v_cvt_pk_bf16_f32 v119, v120, v121
	ds_write2_b64 v116, v[118:119], v[114:115] offset0:32 offset1:36
	v_cvt_pk_bf16_f32 v110, v110, v111
	v_cvt_pk_bf16_f32 v111, v112, v113
	ds_write2_b64 v108, v[110:111], v[106:107] offset0:64 offset1:68
	v_cvt_pk_bf16_f32 v102, v102, v103
	v_cvt_pk_bf16_f32 v103, v104, v105
	ds_write2_b64 v100, v[102:103], v[98:99] offset0:96 offset1:100
	v_cvt_pk_bf16_f32 v86, v86, v87
	v_cvt_pk_bf16_f32 v87, v88, v89
	v_cvt_pk_bf16_f32 v82, v82, v83
	v_cvt_pk_bf16_f32 v83, v84, v85
	ds_write2_b64 v116, v[86:87], v[82:83] offset0:64 offset1:68
	v_cvt_pk_bf16_f32 v62, v62, v63
	v_cvt_pk_bf16_f32 v63, v64, v65
	ds_write_b64 v66, v[62:63]
	v_cvt_pk_bf16_f32 v54, v54, v55
	v_cvt_pk_bf16_f32 v55, v56, v57
	ds_write_b64 v58, v[54:55]
	v_cvt_pk_bf16_f32 v46, v46, v47
	v_cvt_pk_bf16_f32 v47, v48, v49
	ds_write_b64 v50, v[46:47]
	v_cvt_pk_bf16_f32 v38, v38, v39
	v_cvt_pk_bf16_f32 v39, v40, v41
	ds_write_b64 v42, v[38:39]
	v_cvt_pk_bf16_f32 v30, v30, v31
	v_cvt_pk_bf16_f32 v31, v32, v33
	ds_write_b64 v34, v[30:31]
	v_cvt_pk_bf16_f32 v22, v22, v23
	v_cvt_pk_bf16_f32 v23, v24, v25
	ds_write_b64 v26, v[22:23]
	v_cvt_pk_bf16_f32 v14, v14, v15
	v_cvt_pk_bf16_f32 v15, v16, v17
	ds_write_b64 v18, v[14:15]
	v_cvt_pk_bf16_f32 v6, v6, v7
	v_cvt_pk_bf16_f32 v7, v8, v9
	ds_write_b64 v10, v[6:7]
	v_cvt_pk_bf16_f32 v3, v4, v5
	ds_write_b64 v1, v[2:3]
	s_waitcnt lgkmcnt(0)
	s_barrier
	v_and_b32_e32 v107, 15, v0
	v_lshrrev_b32_e32 v106, 4, v0
	v_lshrrev_b32_e32 v104, 3, v107
	v_and_b32_e32 v107, 7, v107
	v_lshlrev_b32_e32 v107, 3, v107
	s_lshl_b32 s34, s15, 7
	v_lshl_or_b32 v108, v104, 6, v107
	v_or_b32_e32 v108, s34, v108
	v_lshl_or_b32 v104, v104, 7, v107
	v_lshlrev_b32_e32 v104, 1, v104
	v_mul_u32_u24_e32 v107, 0x1080, v106
	v_add_u32_e32 v104, v104, v107
	s_lshl_b32 s34, s35, 8
	v_lshl_add_u32 v105, v106, 3, s34
	v_mul_u32_u24_e32 v105, 0x1600, v105
	v_lshl_add_u32 v105, v108, 1, v105
	v_mov_b32_e32 v102, 0xbfb8aa3b
	v_mov_b32_e32 v103, 0xbfb8aa3b
	v_cmp_ne_u32_e32 vcc, 0, v106
	s_nop 1
	s_and_saveexec_b64 s[38:39], vcc
	v_add_u32_e32 v107, 0xfffffdf0, v104
	ds_read_b128 v[94:97], v107
	ds_read_b128 v[98:101], v107 offset:128
	s_or_b64 exec, exec, s[38:39]
	s_waitcnt lgkmcnt(0)
	v_lshlrev_b32_e32 v2, 16, v94
	v_and_b32_e32 v3, 0xffff0000, v94
	v_lshlrev_b32_e32 v4, 16, v95
	v_and_b32_e32 v5, 0xffff0000, v95
	v_lshlrev_b32_e32 v6, 16, v96
	v_and_b32_e32 v7, 0xffff0000, v96
	v_lshlrev_b32_e32 v8, 16, v97
	v_and_b32_e32 v9, 0xffff0000, v97
	v_lshlrev_b32_e32 v10, 16, v98
	v_and_b32_e32 v11, 0xffff0000, v98
	v_lshlrev_b32_e32 v12, 16, v99
	v_and_b32_e32 v13, 0xffff0000, v99
	v_lshlrev_b32_e32 v14, 16, v100
	v_and_b32_e32 v15, 0xffff0000, v100
	v_lshlrev_b32_e32 v16, 16, v101
	v_and_b32_e32 v17, 0xffff0000, v101
	v_cmp_eq_u32_e32 vcc, 0, v106
	s_nop 1
	v_cndmask_b32_e64 v2, v2, 0, vcc
	v_cndmask_b32_e64 v3, v3, 0, vcc
	v_cndmask_b32_e64 v4, v4, 0, vcc
	v_cndmask_b32_e64 v5, v5, 0, vcc
	v_cndmask_b32_e64 v6, v6, 0, vcc
	v_cndmask_b32_e64 v7, v7, 0, vcc
	v_cndmask_b32_e64 v8, v8, 0, vcc
	v_cndmask_b32_e64 v9, v9, 0, vcc
	v_cndmask_b32_e64 v10, v10, 0, vcc
	v_cndmask_b32_e64 v11, v11, 0, vcc
	v_cndmask_b32_e64 v12, v12, 0, vcc
	v_cndmask_b32_e64 v13, v13, 0, vcc
	v_cndmask_b32_e64 v14, v14, 0, vcc
	v_cndmask_b32_e64 v15, v15, 0, vcc
	v_cndmask_b32_e64 v16, v16, 0, vcc
	v_cndmask_b32_e64 v17, v17, 0, vcc
	ds_read_b128 v[94:97], v104
	ds_read_b128 v[98:101], v104 offset:128
	s_waitcnt lgkmcnt(0)
	v_lshlrev_b32_e32 v18, 16, v94
	v_and_b32_e32 v19, 0xffff0000, v94
	v_lshlrev_b32_e32 v20, 16, v95
	v_and_b32_e32 v21, 0xffff0000, v95
	v_lshlrev_b32_e32 v22, 16, v96
	v_and_b32_e32 v23, 0xffff0000, v96
	v_lshlrev_b32_e32 v24, 16, v97
	v_and_b32_e32 v25, 0xffff0000, v97
	v_lshlrev_b32_e32 v26, 16, v98
	v_and_b32_e32 v27, 0xffff0000, v98
	v_lshlrev_b32_e32 v28, 16, v99
	v_and_b32_e32 v29, 0xffff0000, v99
	v_lshlrev_b32_e32 v30, 16, v100
	v_and_b32_e32 v31, 0xffff0000, v100
	v_lshlrev_b32_e32 v32, 16, v101
	v_and_b32_e32 v33, 0xffff0000, v101
	ds_read_b128 v[94:97], v104 offset:528
	ds_read_b128 v[98:101], v104 offset:656
	s_waitcnt lgkmcnt(0)
	v_lshlrev_b32_e32 v34, 16, v94
	v_and_b32_e32 v35, 0xffff0000, v94
	v_lshlrev_b32_e32 v36, 16, v95
	v_and_b32_e32 v37, 0xffff0000, v95
	v_lshlrev_b32_e32 v38, 16, v96
	v_and_b32_e32 v39, 0xffff0000, v96
	v_lshlrev_b32_e32 v40, 16, v97
	v_and_b32_e32 v41, 0xffff0000, v97
	v_lshlrev_b32_e32 v42, 16, v98
	v_and_b32_e32 v43, 0xffff0000, v98
	v_lshlrev_b32_e32 v44, 16, v99
	v_and_b32_e32 v45, 0xffff0000, v99
	v_lshlrev_b32_e32 v46, 16, v100
	v_and_b32_e32 v47, 0xffff0000, v100
	v_lshlrev_b32_e32 v48, 16, v101
	v_and_b32_e32 v49, 0xffff0000, v101
	ds_read_b128 v[94:97], v104 offset:1056
	ds_read_b128 v[98:101], v104 offset:1184
	s_waitcnt vmcnt(0)
	v_pk_fma_f32 v[66:67], v[176:177], v[2:3], v[200:201]
	v_pk_fma_f32 v[68:69], v[178:179], v[4:5], v[202:203]
	v_pk_fma_f32 v[70:71], v[180:181], v[6:7], v[204:205]
	v_pk_fma_f32 v[72:73], v[182:183], v[8:9], v[206:207]
	v_pk_fma_f32 v[74:75], v[210:211], v[10:11], v[236:237]
	v_pk_fma_f32 v[76:77], v[212:213], v[12:13], v[238:239]
	v_pk_fma_f32 v[78:79], v[214:215], v[14:15], v[240:241]
	v_pk_fma_f32 v[80:81], v[216:217], v[16:17], v[242:243]
	v_pk_fma_f32 v[66:67], v[184:185], v[18:19], v[66:67]
	v_pk_fma_f32 v[68:69], v[186:187], v[20:21], v[68:69]
	v_pk_fma_f32 v[70:71], v[188:189], v[22:23], v[70:71]
	v_pk_fma_f32 v[72:73], v[190:191], v[24:25], v[72:73]
	v_pk_fma_f32 v[74:75], v[218:219], v[26:27], v[74:75]
	v_pk_fma_f32 v[76:77], v[220:221], v[28:29], v[76:77]
	v_pk_fma_f32 v[78:79], v[222:223], v[30:31], v[78:79]
	v_pk_fma_f32 v[80:81], v[224:225], v[32:33], v[80:81]
	v_pk_fma_f32 v[66:67], v[192:193], v[34:35], v[66:67]
	v_pk_fma_f32 v[68:69], v[194:195], v[36:37], v[68:69]
	v_pk_fma_f32 v[70:71], v[196:197], v[38:39], v[70:71]
	v_pk_fma_f32 v[72:73], v[198:199], v[40:41], v[72:73]
	v_pk_fma_f32 v[74:75], v[228:229], v[42:43], v[74:75]
	v_pk_fma_f32 v[76:77], v[230:231], v[44:45], v[76:77]
	v_pk_fma_f32 v[78:79], v[232:233], v[46:47], v[78:79]
	v_pk_fma_f32 v[80:81], v[234:235], v[48:49], v[80:81]
	v_pk_mul_f32 v[82:83], v[66:67], v[102:103]
	v_pk_mul_f32 v[84:85], v[68:69], v[102:103]
	v_pk_mul_f32 v[86:87], v[70:71], v[102:103]
	v_pk_mul_f32 v[88:89], v[72:73], v[102:103]
	v_exp_f32_e32 v82, v82
	v_exp_f32_e32 v83, v83
	v_exp_f32_e32 v84, v84
	v_exp_f32_e32 v85, v85
	v_exp_f32_e32 v86, v86
	v_exp_f32_e32 v87, v87
	v_exp_f32_e32 v88, v88
	v_exp_f32_e32 v89, v89
	v_pk_add_f32 v[82:83], v[82:83], 1.0 op_sel_hi:[1,0]
	v_pk_add_f32 v[84:85], v[84:85], 1.0 op_sel_hi:[1,0]
	v_pk_add_f32 v[86:87], v[86:87], 1.0 op_sel_hi:[1,0]
	v_pk_add_f32 v[88:89], v[88:89], 1.0 op_sel_hi:[1,0]
	v_rcp_f32_e32 v82, v82
	v_rcp_f32_e32 v83, v83
	v_rcp_f32_e32 v84, v84
	v_rcp_f32_e32 v85, v85
	v_rcp_f32_e32 v86, v86
	v_rcp_f32_e32 v87, v87
	v_rcp_f32_e32 v88, v88
	v_rcp_f32_e32 v89, v89
	s_waitcnt lgkmcnt(0)
	v_lshlrev_b32_e32 v50, 16, v94
	v_and_b32_e32 v51, 0xffff0000, v94
	v_lshlrev_b32_e32 v52, 16, v95
	v_and_b32_e32 v53, 0xffff0000, v95
	v_lshlrev_b32_e32 v54, 16, v96
	v_and_b32_e32 v55, 0xffff0000, v96
	v_lshlrev_b32_e32 v56, 16, v97
	v_and_b32_e32 v57, 0xffff0000, v97
	v_lshlrev_b32_e32 v58, 16, v98
	v_and_b32_e32 v59, 0xffff0000, v98
	v_lshlrev_b32_e32 v60, 16, v99
	v_and_b32_e32 v61, 0xffff0000, v99
	v_lshlrev_b32_e32 v62, 16, v100
	v_and_b32_e32 v63, 0xffff0000, v100
	v_lshlrev_b32_e32 v64, 16, v101
	v_and_b32_e32 v65, 0xffff0000, v101
	ds_read_b128 v[94:97], v104 offset:1584
	ds_read_b128 v[98:101], v104 offset:1712
	v_pk_mul_f32 v[66:67], v[66:67], v[82:83]
	v_pk_mul_f32 v[68:69], v[68:69], v[84:85]
	v_pk_mul_f32 v[70:71], v[70:71], v[86:87]
	v_pk_mul_f32 v[72:73], v[72:73], v[88:89]
	v_pk_mul_f32 v[66:67], v[66:67], v[74:75]
	v_pk_mul_f32 v[68:69], v[68:69], v[76:77]
	v_pk_mul_f32 v[70:71], v[70:71], v[78:79]
	v_pk_mul_f32 v[72:73], v[72:73], v[80:81]
	v_cvt_pk_bf16_f32 v90, v66, v67
	v_cvt_pk_bf16_f32 v91, v68, v69
	v_cvt_pk_bf16_f32 v92, v70, v71
	v_cvt_pk_bf16_f32 v93, v72, v73
	s_and_b32 s36, s35, 3
	s_cmp_eq_u32 s36, 0
	s_cselect_b64 s[38:39], -1, 0
	s_cmp_lt_i32 s35, 32
	s_cselect_b64 vcc, -1, 0
	s_or_b64 s[38:39], s[38:39], vcc
	v_cmp_ne_u32_e32 vcc, 0, v106
	s_nop 1
	s_or_b64 vcc, vcc, s[38:39]
	s_and_saveexec_b64 s[38:39], vcc
	global_store_dwordx4 v105, v[90:93], s[12:13] sc1
	s_or_b64 exec, exec, s[38:39]
	v_add_u32_e32 v105, 0x1600, v105
	v_pk_fma_f32 v[66:67], v[176:177], v[18:19], v[200:201]
	v_pk_fma_f32 v[68:69], v[178:179], v[20:21], v[202:203]
	v_pk_fma_f32 v[70:71], v[180:181], v[22:23], v[204:205]
	v_pk_fma_f32 v[72:73], v[182:183], v[24:25], v[206:207]
	v_pk_fma_f32 v[74:75], v[210:211], v[26:27], v[236:237]
	v_pk_fma_f32 v[76:77], v[212:213], v[28:29], v[238:239]
	v_pk_fma_f32 v[78:79], v[214:215], v[30:31], v[240:241]
	v_pk_fma_f32 v[80:81], v[216:217], v[32:33], v[242:243]
	v_pk_fma_f32 v[66:67], v[184:185], v[34:35], v[66:67]
	v_pk_fma_f32 v[68:69], v[186:187], v[36:37], v[68:69]
	v_pk_fma_f32 v[70:71], v[188:189], v[38:39], v[70:71]
	v_pk_fma_f32 v[72:73], v[190:191], v[40:41], v[72:73]
	v_pk_fma_f32 v[74:75], v[218:219], v[42:43], v[74:75]
	v_pk_fma_f32 v[76:77], v[220:221], v[44:45], v[76:77]
	v_pk_fma_f32 v[78:79], v[222:223], v[46:47], v[78:79]
	v_pk_fma_f32 v[80:81], v[224:225], v[48:49], v[80:81]
	v_pk_fma_f32 v[66:67], v[192:193], v[50:51], v[66:67]
	v_pk_fma_f32 v[68:69], v[194:195], v[52:53], v[68:69]
	v_pk_fma_f32 v[70:71], v[196:197], v[54:55], v[70:71]
	v_pk_fma_f32 v[72:73], v[198:199], v[56:57], v[72:73]
	v_pk_fma_f32 v[74:75], v[228:229], v[58:59], v[74:75]
	v_pk_fma_f32 v[76:77], v[230:231], v[60:61], v[76:77]
	v_pk_fma_f32 v[78:79], v[232:233], v[62:63], v[78:79]
	v_pk_fma_f32 v[80:81], v[234:235], v[64:65], v[80:81]
	v_pk_mul_f32 v[82:83], v[66:67], v[102:103]
	v_pk_mul_f32 v[84:85], v[68:69], v[102:103]
	v_pk_mul_f32 v[86:87], v[70:71], v[102:103]
	v_pk_mul_f32 v[88:89], v[72:73], v[102:103]
	v_exp_f32_e32 v82, v82
	v_exp_f32_e32 v83, v83
	v_exp_f32_e32 v84, v84
	v_exp_f32_e32 v85, v85
	v_exp_f32_e32 v86, v86
	v_exp_f32_e32 v87, v87
	v_exp_f32_e32 v88, v88
	v_exp_f32_e32 v89, v89
	v_pk_add_f32 v[82:83], v[82:83], 1.0 op_sel_hi:[1,0]
	v_pk_add_f32 v[84:85], v[84:85], 1.0 op_sel_hi:[1,0]
	v_pk_add_f32 v[86:87], v[86:87], 1.0 op_sel_hi:[1,0]
	v_pk_add_f32 v[88:89], v[88:89], 1.0 op_sel_hi:[1,0]
	v_rcp_f32_e32 v82, v82
	v_rcp_f32_e32 v83, v83
	v_rcp_f32_e32 v84, v84
	v_rcp_f32_e32 v85, v85
	v_rcp_f32_e32 v86, v86
	v_rcp_f32_e32 v87, v87
	v_rcp_f32_e32 v88, v88
	v_rcp_f32_e32 v89, v89
	s_waitcnt lgkmcnt(0)
	v_lshlrev_b32_e32 v2, 16, v94
	v_and_b32_e32 v3, 0xffff0000, v94
	v_lshlrev_b32_e32 v4, 16, v95
	v_and_b32_e32 v5, 0xffff0000, v95
	v_lshlrev_b32_e32 v6, 16, v96
	v_and_b32_e32 v7, 0xffff0000, v96
	v_lshlrev_b32_e32 v8, 16, v97
	v_and_b32_e32 v9, 0xffff0000, v97
	v_lshlrev_b32_e32 v10, 16, v98
	v_and_b32_e32 v11, 0xffff0000, v98
	v_lshlrev_b32_e32 v12, 16, v99
	v_and_b32_e32 v13, 0xffff0000, v99
	v_lshlrev_b32_e32 v14, 16, v100
	v_and_b32_e32 v15, 0xffff0000, v100
	v_lshlrev_b32_e32 v16, 16, v101
	v_and_b32_e32 v17, 0xffff0000, v101
	ds_read_b128 v[94:97], v104 offset:2112
	ds_read_b128 v[98:101], v104 offset:2240
	v_pk_mul_f32 v[66:67], v[66:67], v[82:83]
	v_pk_mul_f32 v[68:69], v[68:69], v[84:85]
	v_pk_mul_f32 v[70:71], v[70:71], v[86:87]
	v_pk_mul_f32 v[72:73], v[72:73], v[88:89]
	v_pk_mul_f32 v[66:67], v[66:67], v[74:75]
	v_pk_mul_f32 v[68:69], v[68:69], v[76:77]
	v_pk_mul_f32 v[70:71], v[70:71], v[78:79]
	v_pk_mul_f32 v[72:73], v[72:73], v[80:81]
	v_cvt_pk_bf16_f32 v90, v66, v67
	v_cvt_pk_bf16_f32 v91, v68, v69
	v_cvt_pk_bf16_f32 v92, v70, v71
	v_cvt_pk_bf16_f32 v93, v72, v73
	global_store_dwordx4 v105, v[90:93], s[12:13] sc1
	v_add_u32_e32 v105, 0x1600, v105
	v_pk_fma_f32 v[66:67], v[176:177], v[34:35], v[200:201]
	v_pk_fma_f32 v[68:69], v[178:179], v[36:37], v[202:203]
	v_pk_fma_f32 v[70:71], v[180:181], v[38:39], v[204:205]
	v_pk_fma_f32 v[72:73], v[182:183], v[40:41], v[206:207]
	v_pk_fma_f32 v[74:75], v[210:211], v[42:43], v[236:237]
	v_pk_fma_f32 v[76:77], v[212:213], v[44:45], v[238:239]
	v_pk_fma_f32 v[78:79], v[214:215], v[46:47], v[240:241]
	v_pk_fma_f32 v[80:81], v[216:217], v[48:49], v[242:243]
	v_pk_fma_f32 v[66:67], v[184:185], v[50:51], v[66:67]
	v_pk_fma_f32 v[68:69], v[186:187], v[52:53], v[68:69]
	v_pk_fma_f32 v[70:71], v[188:189], v[54:55], v[70:71]
	v_pk_fma_f32 v[72:73], v[190:191], v[56:57], v[72:73]
	v_pk_fma_f32 v[74:75], v[218:219], v[58:59], v[74:75]
	v_pk_fma_f32 v[76:77], v[220:221], v[60:61], v[76:77]
	v_pk_fma_f32 v[78:79], v[222:223], v[62:63], v[78:79]
	v_pk_fma_f32 v[80:81], v[224:225], v[64:65], v[80:81]
	v_pk_fma_f32 v[66:67], v[192:193], v[2:3], v[66:67]
	v_pk_fma_f32 v[68:69], v[194:195], v[4:5], v[68:69]
	v_pk_fma_f32 v[70:71], v[196:197], v[6:7], v[70:71]
	v_pk_fma_f32 v[72:73], v[198:199], v[8:9], v[72:73]
	v_pk_fma_f32 v[74:75], v[228:229], v[10:11], v[74:75]
	v_pk_fma_f32 v[76:77], v[230:231], v[12:13], v[76:77]
	v_pk_fma_f32 v[78:79], v[232:233], v[14:15], v[78:79]
	v_pk_fma_f32 v[80:81], v[234:235], v[16:17], v[80:81]
	v_pk_mul_f32 v[82:83], v[66:67], v[102:103]
	v_pk_mul_f32 v[84:85], v[68:69], v[102:103]
	v_pk_mul_f32 v[86:87], v[70:71], v[102:103]
	v_pk_mul_f32 v[88:89], v[72:73], v[102:103]
	v_exp_f32_e32 v82, v82
	v_exp_f32_e32 v83, v83
	v_exp_f32_e32 v84, v84
	v_exp_f32_e32 v85, v85
	v_exp_f32_e32 v86, v86
	v_exp_f32_e32 v87, v87
	v_exp_f32_e32 v88, v88
	v_exp_f32_e32 v89, v89
	v_pk_add_f32 v[82:83], v[82:83], 1.0 op_sel_hi:[1,0]
	v_pk_add_f32 v[84:85], v[84:85], 1.0 op_sel_hi:[1,0]
	v_pk_add_f32 v[86:87], v[86:87], 1.0 op_sel_hi:[1,0]
	v_pk_add_f32 v[88:89], v[88:89], 1.0 op_sel_hi:[1,0]
	v_rcp_f32_e32 v82, v82
	v_rcp_f32_e32 v83, v83
	v_rcp_f32_e32 v84, v84
	v_rcp_f32_e32 v85, v85
	v_rcp_f32_e32 v86, v86
	v_rcp_f32_e32 v87, v87
	v_rcp_f32_e32 v88, v88
	v_rcp_f32_e32 v89, v89
	s_waitcnt lgkmcnt(0)
	v_lshlrev_b32_e32 v18, 16, v94
	v_and_b32_e32 v19, 0xffff0000, v94
	v_lshlrev_b32_e32 v20, 16, v95
	v_and_b32_e32 v21, 0xffff0000, v95
	v_lshlrev_b32_e32 v22, 16, v96
	v_and_b32_e32 v23, 0xffff0000, v96
	v_lshlrev_b32_e32 v24, 16, v97
	v_and_b32_e32 v25, 0xffff0000, v97
	v_lshlrev_b32_e32 v26, 16, v98
	v_and_b32_e32 v27, 0xffff0000, v98
	v_lshlrev_b32_e32 v28, 16, v99
	v_and_b32_e32 v29, 0xffff0000, v99
	v_lshlrev_b32_e32 v30, 16, v100
	v_and_b32_e32 v31, 0xffff0000, v100
	v_lshlrev_b32_e32 v32, 16, v101
	v_and_b32_e32 v33, 0xffff0000, v101
	ds_read_b128 v[94:97], v104 offset:2640
	ds_read_b128 v[98:101], v104 offset:2768
	v_pk_mul_f32 v[66:67], v[66:67], v[82:83]
	v_pk_mul_f32 v[68:69], v[68:69], v[84:85]
	v_pk_mul_f32 v[70:71], v[70:71], v[86:87]
	v_pk_mul_f32 v[72:73], v[72:73], v[88:89]
	v_pk_mul_f32 v[66:67], v[66:67], v[74:75]
	v_pk_mul_f32 v[68:69], v[68:69], v[76:77]
	v_pk_mul_f32 v[70:71], v[70:71], v[78:79]
	v_pk_mul_f32 v[72:73], v[72:73], v[80:81]
	v_cvt_pk_bf16_f32 v90, v66, v67
	v_cvt_pk_bf16_f32 v91, v68, v69
	v_cvt_pk_bf16_f32 v92, v70, v71
	v_cvt_pk_bf16_f32 v93, v72, v73
	global_store_dwordx4 v105, v[90:93], s[12:13] sc1
	v_add_u32_e32 v105, 0x1600, v105
	v_pk_fma_f32 v[66:67], v[176:177], v[50:51], v[200:201]
	v_pk_fma_f32 v[68:69], v[178:179], v[52:53], v[202:203]
	v_pk_fma_f32 v[70:71], v[180:181], v[54:55], v[204:205]
	v_pk_fma_f32 v[72:73], v[182:183], v[56:57], v[206:207]
	v_pk_fma_f32 v[74:75], v[210:211], v[58:59], v[236:237]
	v_pk_fma_f32 v[76:77], v[212:213], v[60:61], v[238:239]
	v_pk_fma_f32 v[78:79], v[214:215], v[62:63], v[240:241]
	v_pk_fma_f32 v[80:81], v[216:217], v[64:65], v[242:243]
	v_pk_fma_f32 v[66:67], v[184:185], v[2:3], v[66:67]
	v_pk_fma_f32 v[68:69], v[186:187], v[4:5], v[68:69]
	v_pk_fma_f32 v[70:71], v[188:189], v[6:7], v[70:71]
	v_pk_fma_f32 v[72:73], v[190:191], v[8:9], v[72:73]
	v_pk_fma_f32 v[74:75], v[218:219], v[10:11], v[74:75]
	v_pk_fma_f32 v[76:77], v[220:221], v[12:13], v[76:77]
	v_pk_fma_f32 v[78:79], v[222:223], v[14:15], v[78:79]
	v_pk_fma_f32 v[80:81], v[224:225], v[16:17], v[80:81]
	v_pk_fma_f32 v[66:67], v[192:193], v[18:19], v[66:67]
	v_pk_fma_f32 v[68:69], v[194:195], v[20:21], v[68:69]
	v_pk_fma_f32 v[70:71], v[196:197], v[22:23], v[70:71]
	v_pk_fma_f32 v[72:73], v[198:199], v[24:25], v[72:73]
	v_pk_fma_f32 v[74:75], v[228:229], v[26:27], v[74:75]
	v_pk_fma_f32 v[76:77], v[230:231], v[28:29], v[76:77]
	v_pk_fma_f32 v[78:79], v[232:233], v[30:31], v[78:79]
	v_pk_fma_f32 v[80:81], v[234:235], v[32:33], v[80:81]
	v_pk_mul_f32 v[82:83], v[66:67], v[102:103]
	v_pk_mul_f32 v[84:85], v[68:69], v[102:103]
	v_pk_mul_f32 v[86:87], v[70:71], v[102:103]
	v_pk_mul_f32 v[88:89], v[72:73], v[102:103]
	v_exp_f32_e32 v82, v82
	v_exp_f32_e32 v83, v83
	v_exp_f32_e32 v84, v84
	v_exp_f32_e32 v85, v85
	v_exp_f32_e32 v86, v86
	v_exp_f32_e32 v87, v87
	v_exp_f32_e32 v88, v88
	v_exp_f32_e32 v89, v89
	v_pk_add_f32 v[82:83], v[82:83], 1.0 op_sel_hi:[1,0]
	v_pk_add_f32 v[84:85], v[84:85], 1.0 op_sel_hi:[1,0]
	v_pk_add_f32 v[86:87], v[86:87], 1.0 op_sel_hi:[1,0]
	v_pk_add_f32 v[88:89], v[88:89], 1.0 op_sel_hi:[1,0]
	v_rcp_f32_e32 v82, v82
	v_rcp_f32_e32 v83, v83
	v_rcp_f32_e32 v84, v84
	v_rcp_f32_e32 v85, v85
	v_rcp_f32_e32 v86, v86
	v_rcp_f32_e32 v87, v87
	v_rcp_f32_e32 v88, v88
	v_rcp_f32_e32 v89, v89
	s_waitcnt lgkmcnt(0)
	v_lshlrev_b32_e32 v34, 16, v94
	v_and_b32_e32 v35, 0xffff0000, v94
	v_lshlrev_b32_e32 v36, 16, v95
	v_and_b32_e32 v37, 0xffff0000, v95
	v_lshlrev_b32_e32 v38, 16, v96
	v_and_b32_e32 v39, 0xffff0000, v96
	v_lshlrev_b32_e32 v40, 16, v97
	v_and_b32_e32 v41, 0xffff0000, v97
	v_lshlrev_b32_e32 v42, 16, v98
	v_and_b32_e32 v43, 0xffff0000, v98
	v_lshlrev_b32_e32 v44, 16, v99
	v_and_b32_e32 v45, 0xffff0000, v99
	v_lshlrev_b32_e32 v46, 16, v100
	v_and_b32_e32 v47, 0xffff0000, v100
	v_lshlrev_b32_e32 v48, 16, v101
	v_and_b32_e32 v49, 0xffff0000, v101
	ds_read_b128 v[94:97], v104 offset:3168
	ds_read_b128 v[98:101], v104 offset:3296
	v_pk_mul_f32 v[66:67], v[66:67], v[82:83]
	v_pk_mul_f32 v[68:69], v[68:69], v[84:85]
	v_pk_mul_f32 v[70:71], v[70:71], v[86:87]
	v_pk_mul_f32 v[72:73], v[72:73], v[88:89]
	v_pk_mul_f32 v[66:67], v[66:67], v[74:75]
	v_pk_mul_f32 v[68:69], v[68:69], v[76:77]
	v_pk_mul_f32 v[70:71], v[70:71], v[78:79]
	v_pk_mul_f32 v[72:73], v[72:73], v[80:81]
	v_cvt_pk_bf16_f32 v90, v66, v67
	v_cvt_pk_bf16_f32 v91, v68, v69
	v_cvt_pk_bf16_f32 v92, v70, v71
	v_cvt_pk_bf16_f32 v93, v72, v73
	global_store_dwordx4 v105, v[90:93], s[12:13] sc1
	v_add_u32_e32 v105, 0x1600, v105
	v_pk_fma_f32 v[66:67], v[176:177], v[2:3], v[200:201]
	v_pk_fma_f32 v[68:69], v[178:179], v[4:5], v[202:203]
	v_pk_fma_f32 v[70:71], v[180:181], v[6:7], v[204:205]
	v_pk_fma_f32 v[72:73], v[182:183], v[8:9], v[206:207]
	v_pk_fma_f32 v[74:75], v[210:211], v[10:11], v[236:237]
	v_pk_fma_f32 v[76:77], v[212:213], v[12:13], v[238:239]
	v_pk_fma_f32 v[78:79], v[214:215], v[14:15], v[240:241]
	v_pk_fma_f32 v[80:81], v[216:217], v[16:17], v[242:243]
	v_pk_fma_f32 v[66:67], v[184:185], v[18:19], v[66:67]
	v_pk_fma_f32 v[68:69], v[186:187], v[20:21], v[68:69]
	v_pk_fma_f32 v[70:71], v[188:189], v[22:23], v[70:71]
	v_pk_fma_f32 v[72:73], v[190:191], v[24:25], v[72:73]
	v_pk_fma_f32 v[74:75], v[218:219], v[26:27], v[74:75]
	v_pk_fma_f32 v[76:77], v[220:221], v[28:29], v[76:77]
	v_pk_fma_f32 v[78:79], v[222:223], v[30:31], v[78:79]
	v_pk_fma_f32 v[80:81], v[224:225], v[32:33], v[80:81]
	v_pk_fma_f32 v[66:67], v[192:193], v[34:35], v[66:67]
	v_pk_fma_f32 v[68:69], v[194:195], v[36:37], v[68:69]
	v_pk_fma_f32 v[70:71], v[196:197], v[38:39], v[70:71]
	v_pk_fma_f32 v[72:73], v[198:199], v[40:41], v[72:73]
	v_pk_fma_f32 v[74:75], v[228:229], v[42:43], v[74:75]
	v_pk_fma_f32 v[76:77], v[230:231], v[44:45], v[76:77]
	v_pk_fma_f32 v[78:79], v[232:233], v[46:47], v[78:79]
	v_pk_fma_f32 v[80:81], v[234:235], v[48:49], v[80:81]
	v_pk_mul_f32 v[82:83], v[66:67], v[102:103]
	v_pk_mul_f32 v[84:85], v[68:69], v[102:103]
	v_pk_mul_f32 v[86:87], v[70:71], v[102:103]
	v_pk_mul_f32 v[88:89], v[72:73], v[102:103]
	v_exp_f32_e32 v82, v82
	v_exp_f32_e32 v83, v83
	v_exp_f32_e32 v84, v84
	v_exp_f32_e32 v85, v85
	v_exp_f32_e32 v86, v86
	v_exp_f32_e32 v87, v87
	v_exp_f32_e32 v88, v88
	v_exp_f32_e32 v89, v89
	v_pk_add_f32 v[82:83], v[82:83], 1.0 op_sel_hi:[1,0]
	v_pk_add_f32 v[84:85], v[84:85], 1.0 op_sel_hi:[1,0]
	v_pk_add_f32 v[86:87], v[86:87], 1.0 op_sel_hi:[1,0]
	v_pk_add_f32 v[88:89], v[88:89], 1.0 op_sel_hi:[1,0]
	v_rcp_f32_e32 v82, v82
	v_rcp_f32_e32 v83, v83
	v_rcp_f32_e32 v84, v84
	v_rcp_f32_e32 v85, v85
	v_rcp_f32_e32 v86, v86
	v_rcp_f32_e32 v87, v87
	v_rcp_f32_e32 v88, v88
	v_rcp_f32_e32 v89, v89
	s_waitcnt lgkmcnt(0)
	v_lshlrev_b32_e32 v50, 16, v94
	v_and_b32_e32 v51, 0xffff0000, v94
	v_lshlrev_b32_e32 v52, 16, v95
	v_and_b32_e32 v53, 0xffff0000, v95
	v_lshlrev_b32_e32 v54, 16, v96
	v_and_b32_e32 v55, 0xffff0000, v96
	v_lshlrev_b32_e32 v56, 16, v97
	v_and_b32_e32 v57, 0xffff0000, v97
	v_lshlrev_b32_e32 v58, 16, v98
	v_and_b32_e32 v59, 0xffff0000, v98
	v_lshlrev_b32_e32 v60, 16, v99
	v_and_b32_e32 v61, 0xffff0000, v99
	v_lshlrev_b32_e32 v62, 16, v100
	v_and_b32_e32 v63, 0xffff0000, v100
	v_lshlrev_b32_e32 v64, 16, v101
	v_and_b32_e32 v65, 0xffff0000, v101
	ds_read_b128 v[94:97], v104 offset:3696
	ds_read_b128 v[98:101], v104 offset:3824
	v_pk_mul_f32 v[66:67], v[66:67], v[82:83]
	v_pk_mul_f32 v[68:69], v[68:69], v[84:85]
	v_pk_mul_f32 v[70:71], v[70:71], v[86:87]
	v_pk_mul_f32 v[72:73], v[72:73], v[88:89]
	v_pk_mul_f32 v[66:67], v[66:67], v[74:75]
	v_pk_mul_f32 v[68:69], v[68:69], v[76:77]
	v_pk_mul_f32 v[70:71], v[70:71], v[78:79]
	v_pk_mul_f32 v[72:73], v[72:73], v[80:81]
	v_cvt_pk_bf16_f32 v90, v66, v67
	v_cvt_pk_bf16_f32 v91, v68, v69
	v_cvt_pk_bf16_f32 v92, v70, v71
	v_cvt_pk_bf16_f32 v93, v72, v73
	global_store_dwordx4 v105, v[90:93], s[12:13] sc1
	v_add_u32_e32 v105, 0x1600, v105
	v_pk_fma_f32 v[66:67], v[176:177], v[18:19], v[200:201]
	v_pk_fma_f32 v[68:69], v[178:179], v[20:21], v[202:203]
	v_pk_fma_f32 v[70:71], v[180:181], v[22:23], v[204:205]
	v_pk_fma_f32 v[72:73], v[182:183], v[24:25], v[206:207]
	v_pk_fma_f32 v[74:75], v[210:211], v[26:27], v[236:237]
	v_pk_fma_f32 v[76:77], v[212:213], v[28:29], v[238:239]
	v_pk_fma_f32 v[78:79], v[214:215], v[30:31], v[240:241]
	v_pk_fma_f32 v[80:81], v[216:217], v[32:33], v[242:243]
	v_pk_fma_f32 v[66:67], v[184:185], v[34:35], v[66:67]
	v_pk_fma_f32 v[68:69], v[186:187], v[36:37], v[68:69]
	v_pk_fma_f32 v[70:71], v[188:189], v[38:39], v[70:71]
	v_pk_fma_f32 v[72:73], v[190:191], v[40:41], v[72:73]
	v_pk_fma_f32 v[74:75], v[218:219], v[42:43], v[74:75]
	v_pk_fma_f32 v[76:77], v[220:221], v[44:45], v[76:77]
	v_pk_fma_f32 v[78:79], v[222:223], v[46:47], v[78:79]
	v_pk_fma_f32 v[80:81], v[224:225], v[48:49], v[80:81]
	v_pk_fma_f32 v[66:67], v[192:193], v[50:51], v[66:67]
	v_pk_fma_f32 v[68:69], v[194:195], v[52:53], v[68:69]
	v_pk_fma_f32 v[70:71], v[196:197], v[54:55], v[70:71]
	v_pk_fma_f32 v[72:73], v[198:199], v[56:57], v[72:73]
	v_pk_fma_f32 v[74:75], v[228:229], v[58:59], v[74:75]
	v_pk_fma_f32 v[76:77], v[230:231], v[60:61], v[76:77]
	v_pk_fma_f32 v[78:79], v[232:233], v[62:63], v[78:79]
	v_pk_fma_f32 v[80:81], v[234:235], v[64:65], v[80:81]
	v_pk_mul_f32 v[82:83], v[66:67], v[102:103]
	v_pk_mul_f32 v[84:85], v[68:69], v[102:103]
	v_pk_mul_f32 v[86:87], v[70:71], v[102:103]
	v_pk_mul_f32 v[88:89], v[72:73], v[102:103]
	v_exp_f32_e32 v82, v82
	v_exp_f32_e32 v83, v83
	v_exp_f32_e32 v84, v84
	v_exp_f32_e32 v85, v85
	v_exp_f32_e32 v86, v86
	v_exp_f32_e32 v87, v87
	v_exp_f32_e32 v88, v88
	v_exp_f32_e32 v89, v89
	v_pk_add_f32 v[82:83], v[82:83], 1.0 op_sel_hi:[1,0]
	v_pk_add_f32 v[84:85], v[84:85], 1.0 op_sel_hi:[1,0]
	v_pk_add_f32 v[86:87], v[86:87], 1.0 op_sel_hi:[1,0]
	v_pk_add_f32 v[88:89], v[88:89], 1.0 op_sel_hi:[1,0]
	v_rcp_f32_e32 v82, v82
	v_rcp_f32_e32 v83, v83
	v_rcp_f32_e32 v84, v84
	v_rcp_f32_e32 v85, v85
	v_rcp_f32_e32 v86, v86
	v_rcp_f32_e32 v87, v87
	v_rcp_f32_e32 v88, v88
	v_rcp_f32_e32 v89, v89
	s_waitcnt lgkmcnt(0)
	v_lshlrev_b32_e32 v2, 16, v94
	v_and_b32_e32 v3, 0xffff0000, v94
	v_lshlrev_b32_e32 v4, 16, v95
	v_and_b32_e32 v5, 0xffff0000, v95
	v_lshlrev_b32_e32 v6, 16, v96
	v_and_b32_e32 v7, 0xffff0000, v96
	v_lshlrev_b32_e32 v8, 16, v97
	v_and_b32_e32 v9, 0xffff0000, v97
	v_lshlrev_b32_e32 v10, 16, v98
	v_and_b32_e32 v11, 0xffff0000, v98
	v_lshlrev_b32_e32 v12, 16, v99
	v_and_b32_e32 v13, 0xffff0000, v99
	v_lshlrev_b32_e32 v14, 16, v100
	v_and_b32_e32 v15, 0xffff0000, v100
	v_lshlrev_b32_e32 v16, 16, v101
	v_and_b32_e32 v17, 0xffff0000, v101
	v_cmp_ne_u32_e32 vcc, 31, v106
	s_nop 1
	s_and_saveexec_b64 s[38:39], vcc
	ds_read_b128 v[94:97], v104 offset:4224
	ds_read_b128 v[98:101], v104 offset:4352
	s_or_b64 exec, exec, s[38:39]
	v_pk_mul_f32 v[66:67], v[66:67], v[82:83]
	v_pk_mul_f32 v[68:69], v[68:69], v[84:85]
	v_pk_mul_f32 v[70:71], v[70:71], v[86:87]
	v_pk_mul_f32 v[72:73], v[72:73], v[88:89]
	v_pk_mul_f32 v[66:67], v[66:67], v[74:75]
	v_pk_mul_f32 v[68:69], v[68:69], v[76:77]
	v_pk_mul_f32 v[70:71], v[70:71], v[78:79]
	v_pk_mul_f32 v[72:73], v[72:73], v[80:81]
	v_cvt_pk_bf16_f32 v90, v66, v67
	v_cvt_pk_bf16_f32 v91, v68, v69
	v_cvt_pk_bf16_f32 v92, v70, v71
	v_cvt_pk_bf16_f32 v93, v72, v73
	global_store_dwordx4 v105, v[90:93], s[12:13] sc1
	v_add_u32_e32 v105, 0x1600, v105
	v_pk_fma_f32 v[66:67], v[176:177], v[34:35], v[200:201]
	v_pk_fma_f32 v[68:69], v[178:179], v[36:37], v[202:203]
	v_pk_fma_f32 v[70:71], v[180:181], v[38:39], v[204:205]
	v_pk_fma_f32 v[72:73], v[182:183], v[40:41], v[206:207]
	v_pk_fma_f32 v[74:75], v[210:211], v[42:43], v[236:237]
	v_pk_fma_f32 v[76:77], v[212:213], v[44:45], v[238:239]
	v_pk_fma_f32 v[78:79], v[214:215], v[46:47], v[240:241]
	v_pk_fma_f32 v[80:81], v[216:217], v[48:49], v[242:243]
	v_pk_fma_f32 v[66:67], v[184:185], v[50:51], v[66:67]
	v_pk_fma_f32 v[68:69], v[186:187], v[52:53], v[68:69]
	v_pk_fma_f32 v[70:71], v[188:189], v[54:55], v[70:71]
	v_pk_fma_f32 v[72:73], v[190:191], v[56:57], v[72:73]
	v_pk_fma_f32 v[74:75], v[218:219], v[58:59], v[74:75]
	v_pk_fma_f32 v[76:77], v[220:221], v[60:61], v[76:77]
	v_pk_fma_f32 v[78:79], v[222:223], v[62:63], v[78:79]
	v_pk_fma_f32 v[80:81], v[224:225], v[64:65], v[80:81]
	v_pk_fma_f32 v[66:67], v[192:193], v[2:3], v[66:67]
	v_pk_fma_f32 v[68:69], v[194:195], v[4:5], v[68:69]
	v_pk_fma_f32 v[70:71], v[196:197], v[6:7], v[70:71]
	v_pk_fma_f32 v[72:73], v[198:199], v[8:9], v[72:73]
	v_pk_fma_f32 v[74:75], v[228:229], v[10:11], v[74:75]
	v_pk_fma_f32 v[76:77], v[230:231], v[12:13], v[76:77]
	v_pk_fma_f32 v[78:79], v[232:233], v[14:15], v[78:79]
	v_pk_fma_f32 v[80:81], v[234:235], v[16:17], v[80:81]
	v_pk_mul_f32 v[82:83], v[66:67], v[102:103]
	v_pk_mul_f32 v[84:85], v[68:69], v[102:103]
	v_pk_mul_f32 v[86:87], v[70:71], v[102:103]
	v_pk_mul_f32 v[88:89], v[72:73], v[102:103]
	v_exp_f32_e32 v82, v82
	v_exp_f32_e32 v83, v83
	v_exp_f32_e32 v84, v84
	v_exp_f32_e32 v85, v85
	v_exp_f32_e32 v86, v86
	v_exp_f32_e32 v87, v87
	v_exp_f32_e32 v88, v88
	v_exp_f32_e32 v89, v89
	v_pk_add_f32 v[82:83], v[82:83], 1.0 op_sel_hi:[1,0]
	v_pk_add_f32 v[84:85], v[84:85], 1.0 op_sel_hi:[1,0]
	v_pk_add_f32 v[86:87], v[86:87], 1.0 op_sel_hi:[1,0]
	v_pk_add_f32 v[88:89], v[88:89], 1.0 op_sel_hi:[1,0]
	v_rcp_f32_e32 v82, v82
	v_rcp_f32_e32 v83, v83
	v_rcp_f32_e32 v84, v84
	v_rcp_f32_e32 v85, v85
	v_rcp_f32_e32 v86, v86
	v_rcp_f32_e32 v87, v87
	v_rcp_f32_e32 v88, v88
	v_rcp_f32_e32 v89, v89
	s_waitcnt lgkmcnt(0)
	v_lshlrev_b32_e32 v18, 16, v94
	v_and_b32_e32 v19, 0xffff0000, v94
	v_lshlrev_b32_e32 v20, 16, v95
	v_and_b32_e32 v21, 0xffff0000, v95
	v_lshlrev_b32_e32 v22, 16, v96
	v_and_b32_e32 v23, 0xffff0000, v96
	v_lshlrev_b32_e32 v24, 16, v97
	v_and_b32_e32 v25, 0xffff0000, v97
	v_lshlrev_b32_e32 v26, 16, v98
	v_and_b32_e32 v27, 0xffff0000, v98
	v_lshlrev_b32_e32 v28, 16, v99
	v_and_b32_e32 v29, 0xffff0000, v99
	v_lshlrev_b32_e32 v30, 16, v100
	v_and_b32_e32 v31, 0xffff0000, v100
	v_lshlrev_b32_e32 v32, 16, v101
	v_and_b32_e32 v33, 0xffff0000, v101
	v_cmp_eq_u32_e32 vcc, 31, v106
	s_nop 1
	v_cndmask_b32_e64 v18, v18, 0, vcc
	v_cndmask_b32_e64 v19, v19, 0, vcc
	v_cndmask_b32_e64 v20, v20, 0, vcc
	v_cndmask_b32_e64 v21, v21, 0, vcc
	v_cndmask_b32_e64 v22, v22, 0, vcc
	v_cndmask_b32_e64 v23, v23, 0, vcc
	v_cndmask_b32_e64 v24, v24, 0, vcc
	v_cndmask_b32_e64 v25, v25, 0, vcc
	v_cndmask_b32_e64 v26, v26, 0, vcc
	v_cndmask_b32_e64 v27, v27, 0, vcc
	v_cndmask_b32_e64 v28, v28, 0, vcc
	v_cndmask_b32_e64 v29, v29, 0, vcc
	v_cndmask_b32_e64 v30, v30, 0, vcc
	v_cndmask_b32_e64 v31, v31, 0, vcc
	v_cndmask_b32_e64 v32, v32, 0, vcc
	v_cndmask_b32_e64 v33, v33, 0, vcc
	v_pk_mul_f32 v[66:67], v[66:67], v[82:83]
	v_pk_mul_f32 v[68:69], v[68:69], v[84:85]
	v_pk_mul_f32 v[70:71], v[70:71], v[86:87]
	v_pk_mul_f32 v[72:73], v[72:73], v[88:89]
	v_pk_mul_f32 v[66:67], v[66:67], v[74:75]
	v_pk_mul_f32 v[68:69], v[68:69], v[76:77]
	v_pk_mul_f32 v[70:71], v[70:71], v[78:79]
	v_pk_mul_f32 v[72:73], v[72:73], v[80:81]
	v_cvt_pk_bf16_f32 v90, v66, v67
	v_cvt_pk_bf16_f32 v91, v68, v69
	v_cvt_pk_bf16_f32 v92, v70, v71
	v_cvt_pk_bf16_f32 v93, v72, v73
	global_store_dwordx4 v105, v[90:93], s[12:13] sc1
	v_add_u32_e32 v105, 0x1600, v105
	v_pk_fma_f32 v[66:67], v[176:177], v[50:51], v[200:201]
	v_pk_fma_f32 v[68:69], v[178:179], v[52:53], v[202:203]
	v_pk_fma_f32 v[70:71], v[180:181], v[54:55], v[204:205]
	v_pk_fma_f32 v[72:73], v[182:183], v[56:57], v[206:207]
	v_pk_fma_f32 v[74:75], v[210:211], v[58:59], v[236:237]
	v_pk_fma_f32 v[76:77], v[212:213], v[60:61], v[238:239]
	v_pk_fma_f32 v[78:79], v[214:215], v[62:63], v[240:241]
	v_pk_fma_f32 v[80:81], v[216:217], v[64:65], v[242:243]
	v_pk_fma_f32 v[66:67], v[184:185], v[2:3], v[66:67]
	v_pk_fma_f32 v[68:69], v[186:187], v[4:5], v[68:69]
	v_pk_fma_f32 v[70:71], v[188:189], v[6:7], v[70:71]
	v_pk_fma_f32 v[72:73], v[190:191], v[8:9], v[72:73]
	v_pk_fma_f32 v[74:75], v[218:219], v[10:11], v[74:75]
	v_pk_fma_f32 v[76:77], v[220:221], v[12:13], v[76:77]
	v_pk_fma_f32 v[78:79], v[222:223], v[14:15], v[78:79]
	v_pk_fma_f32 v[80:81], v[224:225], v[16:17], v[80:81]
	v_pk_fma_f32 v[66:67], v[192:193], v[18:19], v[66:67]
	v_pk_fma_f32 v[68:69], v[194:195], v[20:21], v[68:69]
	v_pk_fma_f32 v[70:71], v[196:197], v[22:23], v[70:71]
	v_pk_fma_f32 v[72:73], v[198:199], v[24:25], v[72:73]
	v_pk_fma_f32 v[74:75], v[228:229], v[26:27], v[74:75]
	v_pk_fma_f32 v[76:77], v[230:231], v[28:29], v[76:77]
	v_pk_fma_f32 v[78:79], v[232:233], v[30:31], v[78:79]
	v_pk_fma_f32 v[80:81], v[234:235], v[32:33], v[80:81]
	v_pk_mul_f32 v[82:83], v[66:67], v[102:103]
	v_pk_mul_f32 v[84:85], v[68:69], v[102:103]
	v_pk_mul_f32 v[86:87], v[70:71], v[102:103]
	v_pk_mul_f32 v[88:89], v[72:73], v[102:103]
	v_exp_f32_e32 v82, v82
	v_exp_f32_e32 v83, v83
	v_exp_f32_e32 v84, v84
	v_exp_f32_e32 v85, v85
	v_exp_f32_e32 v86, v86
	v_exp_f32_e32 v87, v87
	v_exp_f32_e32 v88, v88
	v_exp_f32_e32 v89, v89
	v_pk_add_f32 v[82:83], v[82:83], 1.0 op_sel_hi:[1,0]
	v_pk_add_f32 v[84:85], v[84:85], 1.0 op_sel_hi:[1,0]
	v_pk_add_f32 v[86:87], v[86:87], 1.0 op_sel_hi:[1,0]
	v_pk_add_f32 v[88:89], v[88:89], 1.0 op_sel_hi:[1,0]
	v_rcp_f32_e32 v82, v82
	v_rcp_f32_e32 v83, v83
	v_rcp_f32_e32 v84, v84
	v_rcp_f32_e32 v85, v85
	v_rcp_f32_e32 v86, v86
	v_rcp_f32_e32 v87, v87
	v_rcp_f32_e32 v88, v88
	v_rcp_f32_e32 v89, v89
	v_pk_mul_f32 v[66:67], v[66:67], v[82:83]
	v_pk_mul_f32 v[68:69], v[68:69], v[84:85]
	v_pk_mul_f32 v[70:71], v[70:71], v[86:87]
	v_pk_mul_f32 v[72:73], v[72:73], v[88:89]
	v_pk_mul_f32 v[66:67], v[66:67], v[74:75]
	v_pk_mul_f32 v[68:69], v[68:69], v[76:77]
	v_pk_mul_f32 v[70:71], v[70:71], v[78:79]
	v_pk_mul_f32 v[72:73], v[72:73], v[80:81]
	v_cvt_pk_bf16_f32 v90, v66, v67
	v_cvt_pk_bf16_f32 v91, v68, v69
	v_cvt_pk_bf16_f32 v92, v70, v71
	v_cvt_pk_bf16_f32 v93, v72, v73
	s_and_b32 s36, s35, 3
	s_cmp_eq_u32 s36, 3
	s_cselect_b64 s[38:39], -1, 0
	s_cmp_lt_i32 s35, 32
	s_cselect_b64 vcc, -1, 0
	s_or_b64 s[38:39], s[38:39], vcc
	v_cmp_ne_u32_e32 vcc, 31, v106
	s_nop 1
	s_or_b64 vcc, vcc, s[38:39]
	s_and_saveexec_b64 s[38:39], vcc
	global_store_dwordx4 v105, v[90:93], s[12:13] sc1
	s_or_b64 exec, exec, s[38:39]
	v_mov_b32_e32 v74, v0
	s_cmp_lt_i32 s35, 32
	s_cselect_b64 s[4:5], -1, 0
	s_mov_b64 s[6:7], exec
